# P1 epilogue: 16 tanh-gelu blocks rewritten with packed f32 ops (68 -> 44 VALU per 8 accumulators, same op order, bit-identical)
# baseline (speedup 1.0000x reference)
; #define PG8_STAGE(bufoff, gbase, voff) do { _Pragma("unroll") for (int _i = 0; _i < 2; ++_i) \
;         __builtin_amdgcn_global_load_lds((const unsigned*)((const char*)(gbase) + (voff)[_i]), (LAS unsigned*)(lds + (bufoff) + ldsw + _i * 8192), 16, 0, 0); } while (0)
; #define PG8_LDA(dst, b, h) do { _Pragma("unroll") for (int m = 0; m < 4; ++m) _Pragma("unroll") for (int k = 0; k < 2; ++k) dst[m][k] = *(const LAS bf16x8*)(lds + PG8_SA(b, h) + aoff + m * 2048 + k * 1024); } while (0)
; #define PG8_LDB(dst, b, h) do { _Pragma("unroll") for (int n = 0; n < 2; ++n) _Pragma("unroll") for (int k = 0; k < 2; ++k) dst[n][k] = *(const LAS bf16x8*)(lds + PG8_SB(b, h) + boff + n * 2048 + k * 1024); } while (0)
; #define PG8_MMA(ai, bj, At, Bt) do { __builtin_amdgcn_s_setprio(1); _Pragma("unroll") for (int m = 0; m < 4; ++m) _Pragma("unroll") for (int n = 0; n < 2; ++n) _Pragma("unroll") for (int k = 0; k < 2; ++k) \
;         acc[ai][bj][m][n] = __builtin_amdgcn_mfma_f32_16x16x32_bf16(Bt[n][k], At[m][k], acc[ai][bj][m][n], 0, 0, 0); __builtin_amdgcn_s_setprio(0); } while (0)
; #define PG8_WAIT_V(n) asm volatile("s_waitcnt vmcnt(" #n ")" ::: "memory")
; #define PG8_WAIT_L(n) asm volatile("s_waitcnt lgkmcnt(" #n ")" ::: "memory")
; #define PG8_BAR __builtin_amdgcn_s_barrier()
; #define PG8_SCHED __builtin_amdgcn_sched_barrier(0)
; template <class Epi>
; __device__ __forceinline__ void gemm_phase(LAS unsigned char* lds, const Gemm g, const StaticOrder& S, const Epi& E) {
;     ...
;             PG8_LDB(B0, 0, 0); PG8_SCHED; PG8_LDA(At, 0, 0); PG8_STAGE(PG8_SA(1, 1), a1 + hstepA, voffA);
;             PG8_WAIT_L(8); PG8_BAR; PG8_WAIT_L(0); PG8_MMA(0, 0, At, B0); PG8_BAR; PG8_SCHED;
;             PG8_LDB(B1, 0, 1); PG8_STAGE(PG8_SB(0, 0), b2, voffB);
;             PG8_BAR; PG8_WAIT_L(0); PG8_MMA(0, 1, At, B1); PG8_BAR;
;             PG8_LDA(At, 0, 1); PG8_STAGE(PG8_SA(0, 0), a2, voffA);
;             PG8_BAR; PG8_WAIT_L(0); PG8_MMA(1, 0, At, B0); PG8_BAR; PG8_SCHED;
;             PG8_STAGE(PG8_SB(0, 1), b2 + hstepB, voffB);
;             PG8_WAIT_V(6); PG8_BAR; PG8_MMA(1, 1, At, B1); PG8_BAR;
.LBB0_119:
	s_add_u32 s55, s62, 0xfffc0080
	s_addc_u32 s61, s63, -1
	s_cmp_eq_u32 s33, 12
	s_cselect_b32 s67, s57, s61
	s_cselect_b32 s66, s56, s55
	s_cselect_b32 s65, s59, s31
	s_cselect_b32 s64, s58, s9
	ds_read_b128 v[146:149], v154
	ds_read_b128 v[158:161], v154 offset:1024
	ds_read_b128 v[162:165], v154 offset:2048
	ds_read_b128 v[166:169], v154 offset:3072
	ds_read_b128 v[170:173], v155
	ds_read_b128 v[174:177], v155 offset:1024
	ds_read_b128 v[178:181], v155 offset:2048
	ds_read_b128 v[182:185], v155 offset:3072
	ds_read_b128 v[186:189], v155 offset:4096
	ds_read_b128 v[190:193], v155 offset:5120
	ds_read_b128 v[194:197], v155 offset:6144
	ds_read_b128 v[198:201], v155 offset:7168
	ds_read_b128 v[202:205], v156
	ds_read_b128 v[206:209], v156 offset:1024
	ds_read_b128 v[210:213], v156 offset:2048
	ds_read_b128 v[214:217], v156 offset:3072
	s_add_i32 m0, s68, 0xc000
	v_lshl_add_u64 v[242:243], s[62:63], 0, v[138:139]
	global_load_lds_dwordx4 v[242:243], off
	s_add_i32 m0, s68, 0xe000
	v_lshl_add_u64 v[242:243], s[62:63], 0, v[140:141]
	global_load_lds_dwordx4 v[242:243], off
	s_waitcnt vmcnt(8) lgkmcnt(0)
	s_barrier
	v_mfma_f32_16x16x32_bf16 v[124:127], v[146:149], v[170:173], v[124:127]
	v_mfma_f32_16x16x32_bf16 v[120:123], v[162:165], v[170:173], v[120:123]
	v_mfma_f32_16x16x32_bf16 v[108:111], v[146:149], v[178:181], v[108:111]
	v_mfma_f32_16x16x32_bf16 v[104:107], v[162:165], v[178:181], v[104:107]
	v_mfma_f32_16x16x32_bf16 v[92:95], v[146:149], v[186:189], v[92:95]
	v_mfma_f32_16x16x32_bf16 v[88:91], v[162:165], v[186:189], v[88:91]
	v_mfma_f32_16x16x32_bf16 v[76:79], v[146:149], v[194:197], v[76:79]
	v_mfma_f32_16x16x32_bf16 v[72:75], v[162:165], v[194:197], v[72:75]
	v_mfma_f32_16x16x32_bf16 v[124:127], v[158:161], v[174:177], v[124:127]
	v_mfma_f32_16x16x32_bf16 v[120:123], v[166:169], v[174:177], v[120:123]
	v_mfma_f32_16x16x32_bf16 v[108:111], v[158:161], v[182:185], v[108:111]
	v_mfma_f32_16x16x32_bf16 v[104:107], v[166:169], v[182:185], v[104:107]
	v_mfma_f32_16x16x32_bf16 v[92:95], v[158:161], v[190:193], v[92:95]
	v_mfma_f32_16x16x32_bf16 v[88:91], v[166:169], v[190:193], v[88:91]
	v_mfma_f32_16x16x32_bf16 v[76:79], v[158:161], v[198:201], v[76:79]
	v_mfma_f32_16x16x32_bf16 v[72:75], v[166:169], v[198:201], v[72:75]
	v_mfma_f32_16x16x32_bf16 v[116:119], v[202:205], v[170:173], v[116:119]
	v_mfma_f32_16x16x32_bf16 v[112:115], v[210:213], v[170:173], v[112:115]
	v_mfma_f32_16x16x32_bf16 v[100:103], v[202:205], v[178:181], v[100:103]
	v_mfma_f32_16x16x32_bf16 v[96:99], v[210:213], v[178:181], v[96:99]
	v_mfma_f32_16x16x32_bf16 v[84:87], v[202:205], v[186:189], v[84:87]
	v_mfma_f32_16x16x32_bf16 v[80:83], v[210:213], v[186:189], v[80:83]
	v_mfma_f32_16x16x32_bf16 v[68:71], v[202:205], v[194:197], v[68:71]
	v_mfma_f32_16x16x32_bf16 v[64:67], v[210:213], v[194:197], v[64:67]
	v_mfma_f32_16x16x32_bf16 v[116:119], v[206:209], v[174:177], v[116:119]
	v_mfma_f32_16x16x32_bf16 v[112:115], v[214:217], v[174:177], v[112:115]
	v_mfma_f32_16x16x32_bf16 v[100:103], v[206:209], v[182:185], v[100:103]
	v_mfma_f32_16x16x32_bf16 v[96:99], v[214:217], v[182:185], v[96:99]
	v_mfma_f32_16x16x32_bf16 v[84:87], v[206:209], v[190:193], v[84:87]
	v_mfma_f32_16x16x32_bf16 v[80:83], v[214:217], v[190:193], v[80:83]
	v_mfma_f32_16x16x32_bf16 v[68:71], v[206:209], v[198:201], v[68:71]
	v_mfma_f32_16x16x32_bf16 v[64:67], v[214:217], v[198:201], v[64:67]
	s_barrier
	ds_read_b128 v[170:173], v155 offset:16384
	ds_read_b128 v[174:177], v155 offset:17408
	ds_read_b128 v[178:181], v155 offset:18432
	ds_read_b128 v[182:185], v155 offset:19456
	ds_read_b128 v[186:189], v155 offset:20480
	ds_read_b128 v[190:193], v155 offset:21504
	ds_read_b128 v[194:197], v155 offset:22528
	ds_read_b128 v[198:201], v155 offset:23552
	s_add_i32 s55, s78, s35
	s_mov_b32 m0, s55
	v_lshl_add_u64 v[218:219], s[64:65], 0, v[132:133]
	global_load_lds_dwordx4 v[218:219], off
	s_add_i32 m0, s55, 0x2000
	v_lshl_add_u64 v[220:221], s[64:65], 0, v[136:137]
	global_load_lds_dwordx4 v[220:221], off
	s_mov_b32 m0, s68
	v_lshl_add_u64 v[222:223], s[66:67], 0, v[130:131]
	global_load_lds_dwordx4 v[222:223], off
	s_mov_b32 m0, s69
	v_lshl_add_u64 v[224:225], s[66:67], 0, v[134:135]
	global_load_lds_dwordx4 v[224:225], off
	s_add_u32 s82, s64, 0x40000
	s_addc_u32 s83, s65, 0
	s_add_i32 s55, s79, s35
	s_mov_b32 m0, s55
	v_lshl_add_u64 v[240:241], s[82:83], 0, v[132:133]
	global_load_lds_dwordx4 v[240:241], off
	s_add_i32 m0, s55, 0x2000
	v_lshl_add_u64 v[240:241], s[82:83], 0, v[136:137]
	global_load_lds_dwordx4 v[240:241], off
	s_waitcnt vmcnt(8) lgkmcnt(0)
	s_barrier
; #define PG8_STAGE(bufoff, gbase, voff) do { _Pragma("unroll") for (int _i = 0; _i < 2; ++_i) \
;         __builtin_amdgcn_global_load_lds((const unsigned*)((const char*)(gbase) + (voff)[_i]), (LAS unsigned*)(lds + (bufoff) + ldsw + _i * 8192), 16, 0, 0); } while (0)
; #define PG8_LDA(dst, b, h) do { _Pragma("unroll") for (int m = 0; m < 4; ++m) _Pragma("unroll") for (int k = 0; k < 2; ++k) dst[m][k] = *(const LAS bf16x8*)(lds + PG8_SA(b, h) + aoff + m * 2048 + k * 1024); } while (0)
; #define PG8_LDB(dst, b, h) do { _Pragma("unroll") for (int n = 0; n < 2; ++n) _Pragma("unroll") for (int k = 0; k < 2; ++k) dst[n][k] = *(const LAS bf16x8*)(lds + PG8_SB(b, h) + boff + n * 2048 + k * 1024); } while (0)
; #define PG8_MMA(ai, bj, At, Bt) do { __builtin_amdgcn_s_setprio(1); _Pragma("unroll") for (int m = 0; m < 4; ++m) _Pragma("unroll") for (int n = 0; n < 2; ++n) _Pragma("unroll") for (int k = 0; k < 2; ++k) \
;         acc[ai][bj][m][n] = __builtin_amdgcn_mfma_f32_16x16x32_bf16(Bt[n][k], At[m][k], acc[ai][bj][m][n], 0, 0, 0); __builtin_amdgcn_s_setprio(0); } while (0)
; #define PG8_WAIT_V(n) asm volatile("s_waitcnt vmcnt(" #n ")" ::: "memory")
; #define PG8_WAIT_L(n) asm volatile("s_waitcnt lgkmcnt(" #n ")" ::: "memory")
; #define PG8_BAR __builtin_amdgcn_s_barrier()
; #define PG8_SCHED __builtin_amdgcn_sched_barrier(0)
; template <class Epi>
; __device__ __forceinline__ void gemm_phase(LAS unsigned char* lds, const Gemm g, const StaticOrder& S, const Epi& E) {
;     ...
;             PG8_WAIT_V(6); PG8_BAR; PG8_MMA(1, 1, At, B1); PG8_BAR;
;             PG8_LDB(B0, 1, 0); PG8_SCHED; PG8_LDA(At, 1, 0); PG8_STAGE(PG8_SA(0, 1), a2 + hstepA, voffA);
;             PG8_WAIT_L(8); PG8_BAR; PG8_WAIT_L(0); PG8_MMA(0, 0, At, B0); PG8_BAR; PG8_SCHED;
;             PG8_LDB(B1, 1, 1); PG8_STAGE(PG8_SB(1, 0), b3, voffB);
;             PG8_BAR; PG8_WAIT_L(0); PG8_MMA(0, 1, At, B1); PG8_BAR;
;             PG8_LDA(At, 1, 1); PG8_STAGE(PG8_SA(1, 0), a3, voffA);
	v_mfma_f32_16x16x32_bf16 v[60:63], v[146:149], v[170:173], v[60:63]
	v_mfma_f32_16x16x32_bf16 v[56:59], v[162:165], v[170:173], v[56:59]
	v_mfma_f32_16x16x32_bf16 v[44:47], v[146:149], v[178:181], v[44:47]
	v_mfma_f32_16x16x32_bf16 v[40:43], v[162:165], v[178:181], v[40:43]
	v_mfma_f32_16x16x32_bf16 v[28:31], v[146:149], v[186:189], v[28:31]
	v_mfma_f32_16x16x32_bf16 v[24:27], v[162:165], v[186:189], v[24:27]
	v_mfma_f32_16x16x32_bf16 v[12:15], v[146:149], v[194:197], v[12:15]
	v_mfma_f32_16x16x32_bf16 v[8:11], v[162:165], v[194:197], v[8:11]
	v_mfma_f32_16x16x32_bf16 v[60:63], v[158:161], v[174:177], v[60:63]
	v_mfma_f32_16x16x32_bf16 v[56:59], v[166:169], v[174:177], v[56:59]
	v_mfma_f32_16x16x32_bf16 v[44:47], v[158:161], v[182:185], v[44:47]
	v_mfma_f32_16x16x32_bf16 v[40:43], v[166:169], v[182:185], v[40:43]
	v_mfma_f32_16x16x32_bf16 v[28:31], v[158:161], v[190:193], v[28:31]
	v_mfma_f32_16x16x32_bf16 v[24:27], v[166:169], v[190:193], v[24:27]
	v_mfma_f32_16x16x32_bf16 v[12:15], v[158:161], v[198:201], v[12:15]
	v_mfma_f32_16x16x32_bf16 v[8:11], v[166:169], v[198:201], v[8:11]
	v_mfma_f32_16x16x32_bf16 v[52:55], v[202:205], v[170:173], v[52:55]
	v_mfma_f32_16x16x32_bf16 v[48:51], v[210:213], v[170:173], v[48:51]
	v_mfma_f32_16x16x32_bf16 v[36:39], v[202:205], v[178:181], v[36:39]
	v_mfma_f32_16x16x32_bf16 v[32:35], v[210:213], v[178:181], v[32:35]
	v_mfma_f32_16x16x32_bf16 v[20:23], v[202:205], v[186:189], v[20:23]
	v_mfma_f32_16x16x32_bf16 v[16:19], v[210:213], v[186:189], v[16:19]
	v_mfma_f32_16x16x32_bf16 v[4:7], v[202:205], v[194:197], v[4:7]
	v_mfma_f32_16x16x32_bf16 v[0:3], v[210:213], v[194:197], v[0:3]
	v_mfma_f32_16x16x32_bf16 v[52:55], v[206:209], v[174:177], v[52:55]
	v_mfma_f32_16x16x32_bf16 v[48:51], v[214:217], v[174:177], v[48:51]
	v_mfma_f32_16x16x32_bf16 v[36:39], v[206:209], v[182:185], v[36:39]
	v_mfma_f32_16x16x32_bf16 v[32:35], v[214:217], v[182:185], v[32:35]
	v_mfma_f32_16x16x32_bf16 v[20:23], v[206:209], v[190:193], v[20:23]
	v_mfma_f32_16x16x32_bf16 v[16:19], v[214:217], v[190:193], v[16:19]
	v_mfma_f32_16x16x32_bf16 v[4:7], v[206:209], v[198:201], v[4:7]
	v_mfma_f32_16x16x32_bf16 v[0:3], v[214:217], v[198:201], v[0:3]
	s_barrier
	s_add_i32 s55, 0, 0x18000
	v_add_u32_e32 v157, s55, v152
	ds_read_b128 v[146:149], v157
	ds_read_b128 v[158:161], v157 offset:1024
	ds_read_b128 v[162:165], v157 offset:2048
	ds_read_b128 v[166:169], v157 offset:3072
	ds_read_b128 v[170:173], v155 offset:32768
	ds_read_b128 v[174:177], v155 offset:33792
	ds_read_b128 v[178:181], v155 offset:34816
	ds_read_b128 v[182:185], v155 offset:35840
	ds_read_b128 v[186:189], v155 offset:36864
	ds_read_b128 v[190:193], v155 offset:37888
	ds_read_b128 v[194:197], v155 offset:38912
	ds_read_b128 v[198:201], v155 offset:39936
	s_add_i32 s98, 0, 0x1c000
	v_add_u32_e32 v246, s98, v152
	ds_read_b128 v[202:205], v246
	ds_read_b128 v[206:209], v246 offset:1024
	ds_read_b128 v[210:213], v246 offset:2048
	ds_read_b128 v[214:217], v246 offset:3072
	s_add_u32 s66, s66, 0x40000
	s_addc_u32 s67, s67, 0
	s_mov_b32 m0, s70
	v_lshl_add_u64 v[244:245], s[66:67], 0, v[130:131]
	global_load_lds_dwordx4 v[244:245], off
	s_mov_b32 m0, s71
	v_lshl_add_u64 v[244:245], s[66:67], 0, v[134:135]
	global_load_lds_dwordx4 v[244:245], off
	s_waitcnt vmcnt(8) lgkmcnt(0)
	s_barrier
	v_mfma_f32_16x16x32_bf16 v[124:127], v[146:149], v[170:173], v[124:127]
	v_mfma_f32_16x16x32_bf16 v[120:123], v[162:165], v[170:173], v[120:123]
	v_mfma_f32_16x16x32_bf16 v[108:111], v[146:149], v[178:181], v[108:111]
	v_mfma_f32_16x16x32_bf16 v[104:107], v[162:165], v[178:181], v[104:107]
	v_mfma_f32_16x16x32_bf16 v[92:95], v[146:149], v[186:189], v[92:95]
	v_mfma_f32_16x16x32_bf16 v[88:91], v[162:165], v[186:189], v[88:91]
	v_mfma_f32_16x16x32_bf16 v[76:79], v[146:149], v[194:197], v[76:79]
	v_mfma_f32_16x16x32_bf16 v[72:75], v[162:165], v[194:197], v[72:75]
	v_mfma_f32_16x16x32_bf16 v[124:127], v[158:161], v[174:177], v[124:127]
	v_mfma_f32_16x16x32_bf16 v[120:123], v[166:169], v[174:177], v[120:123]
	v_mfma_f32_16x16x32_bf16 v[108:111], v[158:161], v[182:185], v[108:111]
	v_mfma_f32_16x16x32_bf16 v[104:107], v[166:169], v[182:185], v[104:107]
	v_mfma_f32_16x16x32_bf16 v[92:95], v[158:161], v[190:193], v[92:95]
	v_mfma_f32_16x16x32_bf16 v[88:91], v[166:169], v[190:193], v[88:91]
	v_mfma_f32_16x16x32_bf16 v[76:79], v[158:161], v[198:201], v[76:79]
	v_mfma_f32_16x16x32_bf16 v[72:75], v[166:169], v[198:201], v[72:75]
	v_mfma_f32_16x16x32_bf16 v[116:119], v[202:205], v[170:173], v[116:119]
	v_mfma_f32_16x16x32_bf16 v[112:115], v[210:213], v[170:173], v[112:115]
	v_mfma_f32_16x16x32_bf16 v[100:103], v[202:205], v[178:181], v[100:103]
	v_mfma_f32_16x16x32_bf16 v[96:99], v[210:213], v[178:181], v[96:99]
	v_mfma_f32_16x16x32_bf16 v[84:87], v[202:205], v[186:189], v[84:87]
	v_mfma_f32_16x16x32_bf16 v[80:83], v[210:213], v[186:189], v[80:83]
	v_mfma_f32_16x16x32_bf16 v[68:71], v[202:205], v[194:197], v[68:71]
	v_mfma_f32_16x16x32_bf16 v[64:67], v[210:213], v[194:197], v[64:67]
	v_mfma_f32_16x16x32_bf16 v[116:119], v[206:209], v[174:177], v[116:119]
	v_mfma_f32_16x16x32_bf16 v[112:115], v[214:217], v[174:177], v[112:115]
	v_mfma_f32_16x16x32_bf16 v[100:103], v[206:209], v[182:185], v[100:103]
	v_mfma_f32_16x16x32_bf16 v[96:99], v[214:217], v[182:185], v[96:99]
	v_mfma_f32_16x16x32_bf16 v[84:87], v[206:209], v[190:193], v[84:87]
	v_mfma_f32_16x16x32_bf16 v[80:83], v[214:217], v[190:193], v[80:83]
	v_mfma_f32_16x16x32_bf16 v[68:71], v[206:209], v[198:201], v[68:71]
	v_mfma_f32_16x16x32_bf16 v[64:67], v[214:217], v[198:201], v[64:67]
	s_barrier
; __device__ __forceinline__ float gelu_t(float x) { return x * __builtin_amdgcn_rcpf(1.f + __expf(-1.5957691216057308f * (x + 0.044715f * x * x * x))); }
; #define PG8_STAGE(bufoff, gbase, voff) do { _Pragma("unroll") for (int _i = 0; _i < 2; ++_i) \
;         __builtin_amdgcn_global_load_lds((const unsigned*)((const char*)(gbase) + (voff)[_i]), (LAS unsigned*)(lds + (bufoff) + ldsw + _i * 8192), 16, 0, 0); } while (0)
; #define PG8_LDA(dst, b, h) do { _Pragma("unroll") for (int m = 0; m < 4; ++m) _Pragma("unroll") for (int k = 0; k < 2; ++k) dst[m][k] = *(const LAS bf16x8*)(lds + PG8_SA(b, h) + aoff + m * 2048 + k * 1024); } while (0)
; #define PG8_MMA(ai, bj, At, Bt) do { __builtin_amdgcn_s_setprio(1); _Pragma("unroll") for (int m = 0; m < 4; ++m) _Pragma("unroll") for (int n = 0; n < 2; ++n) _Pragma("unroll") for (int k = 0; k < 2; ++k) \
;         acc[ai][bj][m][n] = __builtin_amdgcn_mfma_f32_16x16x32_bf16(Bt[n][k], At[m][k], acc[ai][bj][m][n], 0, 0, 0); __builtin_amdgcn_s_setprio(0); } while (0)
; #define PG8_WAIT_V(n) asm volatile("s_waitcnt vmcnt(" #n ")" ::: "memory")
; #define PG8_WAIT_L(n) asm volatile("s_waitcnt lgkmcnt(" #n ")" ::: "memory")
; #define PG8_BAR __builtin_amdgcn_s_barrier()
; #define PG8_SCHED __builtin_amdgcn_sched_barrier(0)
;     __device__ __forceinline__ void operator()(const f32x4 (&acc)[2][2][4][2], const Unit& u, int wr, int wc, int fr, int fq) const {
;     ...
;                 for (int bj = 0; bj < 2; ++bj) { f32x4 v0 = acc[ai][bj][m][0], v1 = acc[ai][bj][m][1];
;                     if (col0 + bj * HALF >= gelu_from) { v0 = (f32x4){gelu_t(v0.x), gelu_t(v0.y), gelu_t(v0.z), gelu_t(v0.w)}; v1 = (f32x4){gelu_t(v1.x), gelu_t(v1.y), gelu_t(v1.z), gelu_t(v1.w)}; }
; template <class Epi>
; __device__ __forceinline__ void gemm_phase(LAS unsigned char* lds, const Gemm g, const StaticOrder& S, const Epi& E) {
;     ...
;             PG8_LDA(At, 1, 1); PG8_STAGE(PG8_SA(1, 0), a3, voffA);
;             PG8_BAR; PG8_WAIT_L(0); PG8_MMA(1, 0, At, B0); PG8_BAR; PG8_SCHED;
;             PG8_STAGE(PG8_SB(1, 1), b3 + hstepB, voffB);
;             PG8_WAIT_V(6); PG8_BAR; PG8_MMA(1, 1, At, B1); PG8_BAR;
;         }
	ds_read_b128 v[170:173], v155 offset:49152
	ds_read_b128 v[174:177], v155 offset:50176
	ds_read_b128 v[178:181], v155 offset:51200
	ds_read_b128 v[182:185], v155 offset:52224
	ds_read_b128 v[186:189], v155 offset:53248
	ds_read_b128 v[190:193], v155 offset:54272
	ds_read_b128 v[194:197], v155 offset:55296
	ds_read_b128 v[198:201], v155 offset:56320
	s_add_i32 s55, s55, s35
	s_mov_b32 m0, s55
	v_lshl_add_u64 v[218:219], v[218:219], 0, s[28:29]
	global_load_lds_dwordx4 v[218:219], off
	s_add_i32 m0, s55, 0x2000
	v_lshl_add_u64 v[218:219], v[220:221], 0, s[28:29]
	global_load_lds_dwordx4 v[218:219], off
	s_mov_b32 m0, s73
	v_lshl_add_u64 v[218:219], v[222:223], 0, s[28:29]
	global_load_lds_dwordx4 v[218:219], off
	s_mov_b32 m0, s74
	v_lshl_add_u64 v[218:219], v[224:225], 0, s[28:29]
	global_load_lds_dwordx4 v[218:219], off
	s_add_u32 s64, s64, 0x40080
	s_addc_u32 s65, s65, 0
	s_add_i32 s55, s98, s35
	s_mov_b32 m0, s55
	v_lshl_add_u64 v[240:241], s[64:65], 0, v[132:133]
	global_load_lds_dwordx4 v[240:241], off
	s_add_i32 m0, s55, 0x2000
	v_lshl_add_u64 v[240:241], s[64:65], 0, v[136:137]
	global_load_lds_dwordx4 v[240:241], off
	s_waitcnt vmcnt(8) lgkmcnt(0)
	s_barrier
	v_mfma_f32_16x16x32_bf16 v[60:63], v[146:149], v[170:173], v[60:63]
	v_mfma_f32_16x16x32_bf16 v[56:59], v[162:165], v[170:173], v[56:59]
	v_mfma_f32_16x16x32_bf16 v[44:47], v[146:149], v[178:181], v[44:47]
	v_mfma_f32_16x16x32_bf16 v[40:43], v[162:165], v[178:181], v[40:43]
	v_mfma_f32_16x16x32_bf16 v[28:31], v[146:149], v[186:189], v[28:31]
	v_mfma_f32_16x16x32_bf16 v[24:27], v[162:165], v[186:189], v[24:27]
	v_mfma_f32_16x16x32_bf16 v[12:15], v[146:149], v[194:197], v[12:15]
	v_mfma_f32_16x16x32_bf16 v[8:11], v[162:165], v[194:197], v[8:11]
	v_mfma_f32_16x16x32_bf16 v[60:63], v[158:161], v[174:177], v[60:63]
	v_mfma_f32_16x16x32_bf16 v[56:59], v[166:169], v[174:177], v[56:59]
	v_mfma_f32_16x16x32_bf16 v[44:47], v[158:161], v[182:185], v[44:47]
	v_mfma_f32_16x16x32_bf16 v[40:43], v[166:169], v[182:185], v[40:43]
	v_mfma_f32_16x16x32_bf16 v[28:31], v[158:161], v[190:193], v[28:31]
	v_mfma_f32_16x16x32_bf16 v[24:27], v[166:169], v[190:193], v[24:27]
	v_mfma_f32_16x16x32_bf16 v[12:15], v[158:161], v[198:201], v[12:15]
	v_mfma_f32_16x16x32_bf16 v[8:11], v[166:169], v[198:201], v[8:11]
	v_mfma_f32_16x16x32_bf16 v[52:55], v[202:205], v[170:173], v[52:55]
	v_mfma_f32_16x16x32_bf16 v[48:51], v[210:213], v[170:173], v[48:51]
	v_mfma_f32_16x16x32_bf16 v[36:39], v[202:205], v[178:181], v[36:39]
	v_mfma_f32_16x16x32_bf16 v[32:35], v[210:213], v[178:181], v[32:35]
	v_mfma_f32_16x16x32_bf16 v[20:23], v[202:205], v[186:189], v[20:23]
	v_mfma_f32_16x16x32_bf16 v[16:19], v[210:213], v[186:189], v[16:19]
	v_mfma_f32_16x16x32_bf16 v[4:7], v[202:205], v[194:197], v[4:7]
	v_mfma_f32_16x16x32_bf16 v[0:3], v[210:213], v[194:197], v[0:3]
	v_mfma_f32_16x16x32_bf16 v[52:55], v[206:209], v[174:177], v[52:55]
	v_mfma_f32_16x16x32_bf16 v[48:51], v[214:217], v[174:177], v[48:51]
	v_mfma_f32_16x16x32_bf16 v[36:39], v[206:209], v[182:185], v[36:39]
	v_mfma_f32_16x16x32_bf16 v[32:35], v[214:217], v[182:185], v[32:35]
	v_mfma_f32_16x16x32_bf16 v[20:23], v[206:209], v[190:193], v[20:23]
	v_mfma_f32_16x16x32_bf16 v[16:19], v[214:217], v[190:193], v[16:19]
	v_mfma_f32_16x16x32_bf16 v[4:7], v[206:209], v[198:201], v[4:7]
	v_mfma_f32_16x16x32_bf16 v[0:3], v[214:217], v[198:201], v[0:3]
	s_add_i32 s33, s33, 2
	s_add_u32 s62, s62, 0x100
	s_addc_u32 s63, s63, 0
	s_add_u32 s9, s9, 0x100
	s_addc_u32 s31, s31, 0
	s_cmp_gt_u32 s33, 13
	s_barrier
	s_cbranch_scc0 .LBB0_119
	s_mov_b32 s98, 0x3d372713
	s_mov_b32 s99, 0x3d372713
	s_mov_b32 s100, 0xbfcc422a
	s_mov_b32 s101, 0xbfcc422a
	v_mov_b32_e32 v238, 0x3fb8aa3b
	v_mov_b32_e32 v239, 1.0
	v_lshl_or_b32 v146, s60, 8, v153
	v_cmp_lt_i32_e32 vcc, s80, v146
	s_and_saveexec_b64 s[60:61], vcc
	s_cbranch_execz .LBB0_122
	v_pk_mul_f32 v[158:159], v[126:127], s[98:99]
	v_pk_mul_f32 v[148:149], v[124:125], s[98:99]
	v_pk_mul_f32 v[162:163], v[122:123], s[98:99]
	v_pk_mul_f32 v[160:161], v[120:121], s[98:99]
	v_pk_mul_f32 v[158:159], v[126:127], v[158:159]
	v_pk_mul_f32 v[148:149], v[124:125], v[148:149]
	v_pk_mul_f32 v[162:163], v[122:123], v[162:163]
	v_pk_mul_f32 v[160:161], v[120:121], v[160:161]
	v_pk_fma_f32 v[158:159], v[126:127], v[158:159], v[126:127]
	v_pk_fma_f32 v[148:149], v[124:125], v[148:149], v[124:125]
	v_pk_fma_f32 v[162:163], v[122:123], v[162:163], v[122:123]
	v_pk_fma_f32 v[160:161], v[120:121], v[160:161], v[120:121]
	v_pk_mul_f32 v[158:159], v[158:159], s[100:101]
	v_pk_mul_f32 v[148:149], v[148:149], s[100:101]
	v_pk_mul_f32 v[162:163], v[162:163], s[100:101]
	v_pk_mul_f32 v[160:161], v[160:161], s[100:101]
	v_pk_mul_f32 v[158:159], v[158:159], v[238:239] op_sel_hi:[1,0]
	v_pk_mul_f32 v[148:149], v[148:149], v[238:239] op_sel_hi:[1,0]
	v_pk_mul_f32 v[162:163], v[162:163], v[238:239] op_sel_hi:[1,0]
	v_pk_mul_f32 v[160:161], v[160:161], v[238:239] op_sel_hi:[1,0]
	v_exp_f32_e32 v158, v158
	v_exp_f32_e32 v159, v159
	v_exp_f32_e32 v148, v148
	v_exp_f32_e32 v149, v149
	v_exp_f32_e32 v162, v162
	v_exp_f32_e32 v163, v163
	v_exp_f32_e32 v160, v160
	v_exp_f32_e32 v161, v161
	v_pk_add_f32 v[158:159], v[158:159], v[238:239] op_sel:[0,1] op_sel_hi:[1,1]
	v_pk_add_f32 v[148:149], v[148:149], v[238:239] op_sel:[0,1] op_sel_hi:[1,1]
	v_pk_add_f32 v[162:163], v[162:163], v[238:239] op_sel:[0,1] op_sel_hi:[1,1]
	v_pk_add_f32 v[160:161], v[160:161], v[238:239] op_sel:[0,1] op_sel_hi:[1,1]
	v_rcp_f32_e32 v158, v158
	v_rcp_f32_e32 v159, v159
	v_rcp_f32_e32 v148, v148
	v_rcp_f32_e32 v149, v149
	v_rcp_f32_e32 v162, v162
	v_rcp_f32_e32 v163, v163
	v_rcp_f32_e32 v160, v160
	v_rcp_f32_e32 v161, v161
	v_pk_mul_f32 v[126:127], v[126:127], v[158:159]
	v_pk_mul_f32 v[124:125], v[124:125], v[148:149]
	v_pk_mul_f32 v[122:123], v[122:123], v[162:163]
	v_pk_mul_f32 v[120:121], v[120:121], v[160:161]
; __device__ __forceinline__ unsigned pk2(float lo, float hi) { unsigned r; asm("v_cvt_pk_bf16_f32 %0, %1, %2" : "=v"(r) : "v"(lo), "v"(hi)); return r; }
; __device__ __forceinline__ float gelu_t(float x) { return x * __builtin_amdgcn_rcpf(1.f + __expf(-1.5957691216057308f * (x + 0.044715f * x * x * x))); }
;     __device__ __forceinline__ void operator()(const f32x4 (&acc)[2][2][4][2], const Unit& u, int wr, int wc, int fr, int fq) const {
;     ...
; #pragma unroll
;         for (int ai = 0; ai < 2; ++ai)
; #pragma unroll
;             for (int m = 0; m < 4; ++m) { const int row = row0 + ai * HALF + m * 16; u16* rowp = O + (size_t)row * ldc + col0;
; #pragma unroll
;                 for (int bj = 0; bj < 2; ++bj) { f32x4 v0 = acc[ai][bj][m][0], v1 = acc[ai][bj][m][1];
;                     if (col0 + bj * HALF >= gelu_from) { v0 = (f32x4){gelu_t(v0.x), gelu_t(v0.y), gelu_t(v0.z), gelu_t(v0.w)}; v1 = (f32x4){gelu_t(v1.x), gelu_t(v1.y), gelu_t(v1.z), gelu_t(v1.w)}; }
;                     u32x4 w; w.x = pk2(v0[0], v0[1]); w.y = pk2(v0[2], v0[3]); w.z = pk2(v1[0], v1[1]); w.w = pk2(v1[2], v1[3]);
;                     *(u32x4*)(rowp + bj * HALF) = w;
;                     if (halo != nullptr && m == 3 && fr >= 14) *(u32x4*)(halo + (size_t)((row >> 6) * 2 + (fr - 14)) * ldc + col0 + bj * HALF) = w; } }
.LBB0_122:
	s_or_b64 exec, exec, s[60:61]
	v_lshl_add_u32 v157, s8, 8, v151
	v_mov_b64_e32 v[148:149], s[4:5]
	v_ashrrev_i32_e32 v147, 31, v146
	v_mad_i64_i32 v[148:149], s[8:9], v157, s81, v[148:149]
	v_cvt_pk_bf16_f32 v124, v124, v125
	v_cvt_pk_bf16_f32 v125, v126, v127
	v_cvt_pk_bf16_f32 v126, v120, v121
	v_or_b32_e32 v120, 0x80, v146
	v_lshl_add_u64 v[148:149], v[146:147], 1, v[148:149]
	v_cmp_lt_i32_e64 s[8:9], s80, v120
	v_cvt_pk_bf16_f32 v127, v122, v123
	global_store_dwordx4 v[148:149], v[124:127], off
	s_and_saveexec_b64 s[60:61], s[8:9]
	s_cbranch_execz .LBB0_124
	v_pk_mul_f32 v[122:123], v[118:119], s[98:99]
	v_pk_mul_f32 v[120:121], v[116:117], s[98:99]
	v_pk_mul_f32 v[126:127], v[114:115], s[98:99]
	v_pk_mul_f32 v[124:125], v[112:113], s[98:99]
	v_pk_mul_f32 v[122:123], v[118:119], v[122:123]
	v_pk_mul_f32 v[120:121], v[116:117], v[120:121]
	v_pk_mul_f32 v[126:127], v[114:115], v[126:127]
	v_pk_mul_f32 v[124:125], v[112:113], v[124:125]
	v_pk_fma_f32 v[122:123], v[118:119], v[122:123], v[118:119]
	v_pk_fma_f32 v[120:121], v[116:117], v[120:121], v[116:117]
	v_pk_fma_f32 v[126:127], v[114:115], v[126:127], v[114:115]
	v_pk_fma_f32 v[124:125], v[112:113], v[124:125], v[112:113]
	v_pk_mul_f32 v[122:123], v[122:123], s[100:101]
	v_pk_mul_f32 v[120:121], v[120:121], s[100:101]
	v_pk_mul_f32 v[126:127], v[126:127], s[100:101]
	v_pk_mul_f32 v[124:125], v[124:125], s[100:101]
	v_pk_mul_f32 v[122:123], v[122:123], v[238:239] op_sel_hi:[1,0]
	v_pk_mul_f32 v[120:121], v[120:121], v[238:239] op_sel_hi:[1,0]
	v_pk_mul_f32 v[126:127], v[126:127], v[238:239] op_sel_hi:[1,0]
	v_pk_mul_f32 v[124:125], v[124:125], v[238:239] op_sel_hi:[1,0]
	v_exp_f32_e32 v122, v122
	v_exp_f32_e32 v123, v123
	v_exp_f32_e32 v120, v120
	v_exp_f32_e32 v121, v121
	v_exp_f32_e32 v126, v126
	v_exp_f32_e32 v127, v127
	v_exp_f32_e32 v124, v124
	v_exp_f32_e32 v125, v125
	v_pk_add_f32 v[122:123], v[122:123], v[238:239] op_sel:[0,1] op_sel_hi:[1,1]
	v_pk_add_f32 v[120:121], v[120:121], v[238:239] op_sel:[0,1] op_sel_hi:[1,1]
	v_pk_add_f32 v[126:127], v[126:127], v[238:239] op_sel:[0,1] op_sel_hi:[1,1]
	v_pk_add_f32 v[124:125], v[124:125], v[238:239] op_sel:[0,1] op_sel_hi:[1,1]
	v_rcp_f32_e32 v122, v122
	v_rcp_f32_e32 v123, v123
	v_rcp_f32_e32 v120, v120
	v_rcp_f32_e32 v121, v121
	v_rcp_f32_e32 v126, v126
	v_rcp_f32_e32 v127, v127
	v_rcp_f32_e32 v124, v124
	v_rcp_f32_e32 v125, v125
	v_pk_mul_f32 v[118:119], v[118:119], v[122:123]
	v_pk_mul_f32 v[116:117], v[116:117], v[120:121]
	v_pk_mul_f32 v[114:115], v[114:115], v[126:127]
	v_pk_mul_f32 v[112:113], v[112:113], v[124:125]
.LBB0_124:
	s_or_b64 exec, exec, s[60:61]
	v_cvt_pk_bf16_f32 v116, v116, v117
	v_cvt_pk_bf16_f32 v117, v118, v119
	v_cvt_pk_bf16_f32 v118, v112, v113
	v_cvt_pk_bf16_f32 v119, v114, v115
	global_store_dwordx4 v[148:149], v[116:119], off offset:256
	s_and_saveexec_b64 s[60:61], vcc
	s_cbranch_execz .LBB0_126
	v_pk_mul_f32 v[114:115], v[110:111], s[98:99]
	v_pk_mul_f32 v[112:113], v[108:109], s[98:99]
	v_pk_mul_f32 v[118:119], v[106:107], s[98:99]
	v_pk_mul_f32 v[116:117], v[104:105], s[98:99]
	v_pk_mul_f32 v[114:115], v[110:111], v[114:115]
	v_pk_mul_f32 v[112:113], v[108:109], v[112:113]
	v_pk_mul_f32 v[118:119], v[106:107], v[118:119]
	v_pk_mul_f32 v[116:117], v[104:105], v[116:117]
	v_pk_fma_f32 v[114:115], v[110:111], v[114:115], v[110:111]
	v_pk_fma_f32 v[112:113], v[108:109], v[112:113], v[108:109]
	v_pk_fma_f32 v[118:119], v[106:107], v[118:119], v[106:107]
	v_pk_fma_f32 v[116:117], v[104:105], v[116:117], v[104:105]
	v_pk_mul_f32 v[114:115], v[114:115], s[100:101]
	v_pk_mul_f32 v[112:113], v[112:113], s[100:101]
	v_pk_mul_f32 v[118:119], v[118:119], s[100:101]
	v_pk_mul_f32 v[116:117], v[116:117], s[100:101]
	v_pk_mul_f32 v[114:115], v[114:115], v[238:239] op_sel_hi:[1,0]
	v_pk_mul_f32 v[112:113], v[112:113], v[238:239] op_sel_hi:[1,0]
	v_pk_mul_f32 v[118:119], v[118:119], v[238:239] op_sel_hi:[1,0]
	v_pk_mul_f32 v[116:117], v[116:117], v[238:239] op_sel_hi:[1,0]
	v_exp_f32_e32 v114, v114
	v_exp_f32_e32 v115, v115
	v_exp_f32_e32 v112, v112
	v_exp_f32_e32 v113, v113
	v_exp_f32_e32 v118, v118
	v_exp_f32_e32 v119, v119
	v_exp_f32_e32 v116, v116
	v_exp_f32_e32 v117, v117
	v_pk_add_f32 v[114:115], v[114:115], v[238:239] op_sel:[0,1] op_sel_hi:[1,1]
	v_pk_add_f32 v[112:113], v[112:113], v[238:239] op_sel:[0,1] op_sel_hi:[1,1]
	v_pk_add_f32 v[118:119], v[118:119], v[238:239] op_sel:[0,1] op_sel_hi:[1,1]
	v_pk_add_f32 v[116:117], v[116:117], v[238:239] op_sel:[0,1] op_sel_hi:[1,1]
	v_rcp_f32_e32 v114, v114
	v_rcp_f32_e32 v115, v115
	v_rcp_f32_e32 v112, v112
	v_rcp_f32_e32 v113, v113
	v_rcp_f32_e32 v118, v118
	v_rcp_f32_e32 v119, v119
	v_rcp_f32_e32 v116, v116
	v_rcp_f32_e32 v117, v117
	v_pk_mul_f32 v[110:111], v[110:111], v[114:115]
	v_pk_mul_f32 v[108:109], v[108:109], v[112:113]
	v_pk_mul_f32 v[106:107], v[106:107], v[118:119]
	v_pk_mul_f32 v[104:105], v[104:105], v[116:117]
; __device__ __forceinline__ unsigned pk2(float lo, float hi) { unsigned r; asm("v_cvt_pk_bf16_f32 %0, %1, %2" : "=v"(r) : "v"(lo), "v"(hi)); return r; }
; __device__ __forceinline__ float gelu_t(float x) { return x * __builtin_amdgcn_rcpf(1.f + __expf(-1.5957691216057308f * (x + 0.044715f * x * x * x))); }
;     __device__ __forceinline__ void operator()(const f32x4 (&acc)[2][2][4][2], const Unit& u, int wr, int wc, int fr, int fq) const {
;     ...
; #pragma unroll
;         for (int ai = 0; ai < 2; ++ai)
; #pragma unroll
;             for (int m = 0; m < 4; ++m) { const int row = row0 + ai * HALF + m * 16; u16* rowp = O + (size_t)row * ldc + col0;
; #pragma unroll
;                 for (int bj = 0; bj < 2; ++bj) { f32x4 v0 = acc[ai][bj][m][0], v1 = acc[ai][bj][m][1];
;                     if (col0 + bj * HALF >= gelu_from) { v0 = (f32x4){gelu_t(v0.x), gelu_t(v0.y), gelu_t(v0.z), gelu_t(v0.w)}; v1 = (f32x4){gelu_t(v1.x), gelu_t(v1.y), gelu_t(v1.z), gelu_t(v1.w)}; }
;                     u32x4 w; w.x = pk2(v0[0], v0[1]); w.y = pk2(v0[2], v0[3]); w.z = pk2(v1[0], v1[1]); w.w = pk2(v1[2], v1[3]);
;                     *(u32x4*)(rowp + bj * HALF) = w;
;                     if (halo != nullptr && m == 3 && fr >= 14) *(u32x4*)(halo + (size_t)((row >> 6) * 2 + (fr - 14)) * ldc + col0 + bj * HALF) = w; } }
.LBB0_126:
	s_or_b64 exec, exec, s[60:61]
	v_or_b32_e32 v114, 16, v157
	v_mov_b64_e32 v[112:113], s[4:5]
	v_mad_i64_i32 v[112:113], s[60:61], v114, s81, v[112:113]
	v_lshl_add_u64 v[112:113], v[146:147], 1, v[112:113]
	v_cvt_pk_bf16_f32 v108, v108, v109
	v_cvt_pk_bf16_f32 v109, v110, v111
	v_cvt_pk_bf16_f32 v110, v104, v105
	v_cvt_pk_bf16_f32 v111, v106, v107
	global_store_dwordx4 v[112:113], v[108:111], off
	s_and_saveexec_b64 s[60:61], s[8:9]
	s_cbranch_execz .LBB0_128
	v_pk_mul_f32 v[106:107], v[102:103], s[98:99]
	v_pk_mul_f32 v[104:105], v[100:101], s[98:99]
	v_pk_mul_f32 v[110:111], v[98:99], s[98:99]
	v_pk_mul_f32 v[108:109], v[96:97], s[98:99]
	v_pk_mul_f32 v[106:107], v[102:103], v[106:107]
	v_pk_mul_f32 v[104:105], v[100:101], v[104:105]
	v_pk_mul_f32 v[110:111], v[98:99], v[110:111]
	v_pk_mul_f32 v[108:109], v[96:97], v[108:109]
	v_pk_fma_f32 v[106:107], v[102:103], v[106:107], v[102:103]
	v_pk_fma_f32 v[104:105], v[100:101], v[104:105], v[100:101]
	v_pk_fma_f32 v[110:111], v[98:99], v[110:111], v[98:99]
	v_pk_fma_f32 v[108:109], v[96:97], v[108:109], v[96:97]
	v_pk_mul_f32 v[106:107], v[106:107], s[100:101]
	v_pk_mul_f32 v[104:105], v[104:105], s[100:101]
	v_pk_mul_f32 v[110:111], v[110:111], s[100:101]
	v_pk_mul_f32 v[108:109], v[108:109], s[100:101]
	v_pk_mul_f32 v[106:107], v[106:107], v[238:239] op_sel_hi:[1,0]
	v_pk_mul_f32 v[104:105], v[104:105], v[238:239] op_sel_hi:[1,0]
	v_pk_mul_f32 v[110:111], v[110:111], v[238:239] op_sel_hi:[1,0]
	v_pk_mul_f32 v[108:109], v[108:109], v[238:239] op_sel_hi:[1,0]
	v_exp_f32_e32 v106, v106
	v_exp_f32_e32 v107, v107
	v_exp_f32_e32 v104, v104
	v_exp_f32_e32 v105, v105
	v_exp_f32_e32 v110, v110
	v_exp_f32_e32 v111, v111
	v_exp_f32_e32 v108, v108
	v_exp_f32_e32 v109, v109
	v_pk_add_f32 v[106:107], v[106:107], v[238:239] op_sel:[0,1] op_sel_hi:[1,1]
	v_pk_add_f32 v[104:105], v[104:105], v[238:239] op_sel:[0,1] op_sel_hi:[1,1]
	v_pk_add_f32 v[110:111], v[110:111], v[238:239] op_sel:[0,1] op_sel_hi:[1,1]
	v_pk_add_f32 v[108:109], v[108:109], v[238:239] op_sel:[0,1] op_sel_hi:[1,1]
	v_rcp_f32_e32 v106, v106
	v_rcp_f32_e32 v107, v107
	v_rcp_f32_e32 v104, v104
	v_rcp_f32_e32 v105, v105
	v_rcp_f32_e32 v110, v110
	v_rcp_f32_e32 v111, v111
	v_rcp_f32_e32 v108, v108
	v_rcp_f32_e32 v109, v109
	v_pk_mul_f32 v[102:103], v[102:103], v[106:107]
	v_pk_mul_f32 v[100:101], v[100:101], v[104:105]
	v_pk_mul_f32 v[98:99], v[98:99], v[110:111]
	v_pk_mul_f32 v[96:97], v[96:97], v[108:109]
.LBB0_128:
	s_or_b64 exec, exec, s[60:61]
	v_cvt_pk_bf16_f32 v100, v100, v101
	v_cvt_pk_bf16_f32 v101, v102, v103
	v_cvt_pk_bf16_f32 v102, v96, v97
	v_cvt_pk_bf16_f32 v103, v98, v99
	global_store_dwordx4 v[112:113], v[100:103], off offset:256
	s_and_saveexec_b64 s[60:61], vcc
	s_cbranch_execz .LBB0_130
	v_pk_mul_f32 v[98:99], v[94:95], s[98:99]
	v_pk_mul_f32 v[96:97], v[92:93], s[98:99]
	v_pk_mul_f32 v[102:103], v[90:91], s[98:99]
	v_pk_mul_f32 v[100:101], v[88:89], s[98:99]
	v_pk_mul_f32 v[98:99], v[94:95], v[98:99]
	v_pk_mul_f32 v[96:97], v[92:93], v[96:97]
	v_pk_mul_f32 v[102:103], v[90:91], v[102:103]
	v_pk_mul_f32 v[100:101], v[88:89], v[100:101]
	v_pk_fma_f32 v[98:99], v[94:95], v[98:99], v[94:95]
	v_pk_fma_f32 v[96:97], v[92:93], v[96:97], v[92:93]
	v_pk_fma_f32 v[102:103], v[90:91], v[102:103], v[90:91]
	v_pk_fma_f32 v[100:101], v[88:89], v[100:101], v[88:89]
	v_pk_mul_f32 v[98:99], v[98:99], s[100:101]
	v_pk_mul_f32 v[96:97], v[96:97], s[100:101]
	v_pk_mul_f32 v[102:103], v[102:103], s[100:101]
	v_pk_mul_f32 v[100:101], v[100:101], s[100:101]
	v_pk_mul_f32 v[98:99], v[98:99], v[238:239] op_sel_hi:[1,0]
	v_pk_mul_f32 v[96:97], v[96:97], v[238:239] op_sel_hi:[1,0]
	v_pk_mul_f32 v[102:103], v[102:103], v[238:239] op_sel_hi:[1,0]
	v_pk_mul_f32 v[100:101], v[100:101], v[238:239] op_sel_hi:[1,0]
	v_exp_f32_e32 v98, v98
	v_exp_f32_e32 v99, v99
	v_exp_f32_e32 v96, v96
	v_exp_f32_e32 v97, v97
	v_exp_f32_e32 v102, v102
	v_exp_f32_e32 v103, v103
	v_exp_f32_e32 v100, v100
	v_exp_f32_e32 v101, v101
	v_pk_add_f32 v[98:99], v[98:99], v[238:239] op_sel:[0,1] op_sel_hi:[1,1]
	v_pk_add_f32 v[96:97], v[96:97], v[238:239] op_sel:[0,1] op_sel_hi:[1,1]
	v_pk_add_f32 v[102:103], v[102:103], v[238:239] op_sel:[0,1] op_sel_hi:[1,1]
	v_pk_add_f32 v[100:101], v[100:101], v[238:239] op_sel:[0,1] op_sel_hi:[1,1]
	v_rcp_f32_e32 v98, v98
	v_rcp_f32_e32 v99, v99
	v_rcp_f32_e32 v96, v96
	v_rcp_f32_e32 v97, v97
	v_rcp_f32_e32 v102, v102
	v_rcp_f32_e32 v103, v103
	v_rcp_f32_e32 v100, v100
	v_rcp_f32_e32 v101, v101
	v_pk_mul_f32 v[94:95], v[94:95], v[98:99]
	v_pk_mul_f32 v[92:93], v[92:93], v[96:97]
	v_pk_mul_f32 v[90:91], v[90:91], v[102:103]
	v_pk_mul_f32 v[88:89], v[88:89], v[100:101]
; __device__ __forceinline__ unsigned pk2(float lo, float hi) { unsigned r; asm("v_cvt_pk_bf16_f32 %0, %1, %2" : "=v"(r) : "v"(lo), "v"(hi)); return r; }
; __device__ __forceinline__ float gelu_t(float x) { return x * __builtin_amdgcn_rcpf(1.f + __expf(-1.5957691216057308f * (x + 0.044715f * x * x * x))); }
;     __device__ __forceinline__ void operator()(const f32x4 (&acc)[2][2][4][2], const Unit& u, int wr, int wc, int fr, int fq) const {
;     ...
; #pragma unroll
;         for (int ai = 0; ai < 2; ++ai)
; #pragma unroll
;             for (int m = 0; m < 4; ++m) { const int row = row0 + ai * HALF + m * 16; u16* rowp = O + (size_t)row * ldc + col0;
; #pragma unroll
;                 for (int bj = 0; bj < 2; ++bj) { f32x4 v0 = acc[ai][bj][m][0], v1 = acc[ai][bj][m][1];
;                     if (col0 + bj * HALF >= gelu_from) { v0 = (f32x4){gelu_t(v0.x), gelu_t(v0.y), gelu_t(v0.z), gelu_t(v0.w)}; v1 = (f32x4){gelu_t(v1.x), gelu_t(v1.y), gelu_t(v1.z), gelu_t(v1.w)}; }
;                     u32x4 w; w.x = pk2(v0[0], v0[1]); w.y = pk2(v0[2], v0[3]); w.z = pk2(v1[0], v1[1]); w.w = pk2(v1[2], v1[3]);
;                     *(u32x4*)(rowp + bj * HALF) = w;
;                     if (halo != nullptr && m == 3 && fr >= 14) *(u32x4*)(halo + (size_t)((row >> 6) * 2 + (fr - 14)) * ldc + col0 + bj * HALF) = w; } }
.LBB0_130:
	s_or_b64 exec, exec, s[60:61]
	v_or_b32_e32 v98, 32, v157
	v_mov_b64_e32 v[96:97], s[4:5]
	v_mad_i64_i32 v[96:97], s[60:61], v98, s81, v[96:97]
	v_lshl_add_u64 v[96:97], v[146:147], 1, v[96:97]
	v_cvt_pk_bf16_f32 v92, v92, v93
	v_cvt_pk_bf16_f32 v93, v94, v95
	v_cvt_pk_bf16_f32 v94, v88, v89
	v_cvt_pk_bf16_f32 v95, v90, v91
	global_store_dwordx4 v[96:97], v[92:95], off
	s_and_saveexec_b64 s[60:61], s[8:9]
	s_cbranch_execz .LBB0_132
	v_pk_mul_f32 v[90:91], v[86:87], s[98:99]
	v_pk_mul_f32 v[88:89], v[84:85], s[98:99]
	v_pk_mul_f32 v[94:95], v[82:83], s[98:99]
	v_pk_mul_f32 v[92:93], v[80:81], s[98:99]
	v_pk_mul_f32 v[90:91], v[86:87], v[90:91]
	v_pk_mul_f32 v[88:89], v[84:85], v[88:89]
	v_pk_mul_f32 v[94:95], v[82:83], v[94:95]
	v_pk_mul_f32 v[92:93], v[80:81], v[92:93]
	v_pk_fma_f32 v[90:91], v[86:87], v[90:91], v[86:87]
	v_pk_fma_f32 v[88:89], v[84:85], v[88:89], v[84:85]
	v_pk_fma_f32 v[94:95], v[82:83], v[94:95], v[82:83]
	v_pk_fma_f32 v[92:93], v[80:81], v[92:93], v[80:81]
	v_pk_mul_f32 v[90:91], v[90:91], s[100:101]
	v_pk_mul_f32 v[88:89], v[88:89], s[100:101]
	v_pk_mul_f32 v[94:95], v[94:95], s[100:101]
	v_pk_mul_f32 v[92:93], v[92:93], s[100:101]
	v_pk_mul_f32 v[90:91], v[90:91], v[238:239] op_sel_hi:[1,0]
	v_pk_mul_f32 v[88:89], v[88:89], v[238:239] op_sel_hi:[1,0]
	v_pk_mul_f32 v[94:95], v[94:95], v[238:239] op_sel_hi:[1,0]
	v_pk_mul_f32 v[92:93], v[92:93], v[238:239] op_sel_hi:[1,0]
	v_exp_f32_e32 v90, v90
	v_exp_f32_e32 v91, v91
	v_exp_f32_e32 v88, v88
	v_exp_f32_e32 v89, v89
	v_exp_f32_e32 v94, v94
	v_exp_f32_e32 v95, v95
	v_exp_f32_e32 v92, v92
	v_exp_f32_e32 v93, v93
	v_pk_add_f32 v[90:91], v[90:91], v[238:239] op_sel:[0,1] op_sel_hi:[1,1]
	v_pk_add_f32 v[88:89], v[88:89], v[238:239] op_sel:[0,1] op_sel_hi:[1,1]
	v_pk_add_f32 v[94:95], v[94:95], v[238:239] op_sel:[0,1] op_sel_hi:[1,1]
	v_pk_add_f32 v[92:93], v[92:93], v[238:239] op_sel:[0,1] op_sel_hi:[1,1]
	v_rcp_f32_e32 v90, v90
	v_rcp_f32_e32 v91, v91
	v_rcp_f32_e32 v88, v88
	v_rcp_f32_e32 v89, v89
	v_rcp_f32_e32 v94, v94
	v_rcp_f32_e32 v95, v95
	v_rcp_f32_e32 v92, v92
	v_rcp_f32_e32 v93, v93
	v_pk_mul_f32 v[86:87], v[86:87], v[90:91]
	v_pk_mul_f32 v[84:85], v[84:85], v[88:89]
	v_pk_mul_f32 v[82:83], v[82:83], v[94:95]
	v_pk_mul_f32 v[80:81], v[80:81], v[92:93]
.LBB0_132:
	s_or_b64 exec, exec, s[60:61]
	v_cvt_pk_bf16_f32 v84, v84, v85
	v_cvt_pk_bf16_f32 v85, v86, v87
	v_cvt_pk_bf16_f32 v86, v80, v81
	v_cvt_pk_bf16_f32 v87, v82, v83
	global_store_dwordx4 v[96:97], v[84:87], off offset:256
	s_and_saveexec_b64 s[60:61], vcc
	s_cbranch_execz .LBB0_134
	v_pk_mul_f32 v[82:83], v[78:79], s[98:99]
	v_pk_mul_f32 v[80:81], v[76:77], s[98:99]
	v_pk_mul_f32 v[86:87], v[74:75], s[98:99]
	v_pk_mul_f32 v[84:85], v[72:73], s[98:99]
	v_pk_mul_f32 v[82:83], v[78:79], v[82:83]
	v_pk_mul_f32 v[80:81], v[76:77], v[80:81]
	v_pk_mul_f32 v[86:87], v[74:75], v[86:87]
	v_pk_mul_f32 v[84:85], v[72:73], v[84:85]
	v_pk_fma_f32 v[82:83], v[78:79], v[82:83], v[78:79]
	v_pk_fma_f32 v[80:81], v[76:77], v[80:81], v[76:77]
	v_pk_fma_f32 v[86:87], v[74:75], v[86:87], v[74:75]
	v_pk_fma_f32 v[84:85], v[72:73], v[84:85], v[72:73]
	v_pk_mul_f32 v[82:83], v[82:83], s[100:101]
	v_pk_mul_f32 v[80:81], v[80:81], s[100:101]
	v_pk_mul_f32 v[86:87], v[86:87], s[100:101]
	v_pk_mul_f32 v[84:85], v[84:85], s[100:101]
	v_pk_mul_f32 v[82:83], v[82:83], v[238:239] op_sel_hi:[1,0]
	v_pk_mul_f32 v[80:81], v[80:81], v[238:239] op_sel_hi:[1,0]
	v_pk_mul_f32 v[86:87], v[86:87], v[238:239] op_sel_hi:[1,0]
	v_pk_mul_f32 v[84:85], v[84:85], v[238:239] op_sel_hi:[1,0]
	v_exp_f32_e32 v82, v82
	v_exp_f32_e32 v83, v83
	v_exp_f32_e32 v80, v80
	v_exp_f32_e32 v81, v81
	v_exp_f32_e32 v86, v86
	v_exp_f32_e32 v87, v87
	v_exp_f32_e32 v84, v84
	v_exp_f32_e32 v85, v85
	v_pk_add_f32 v[82:83], v[82:83], v[238:239] op_sel:[0,1] op_sel_hi:[1,1]
	v_pk_add_f32 v[80:81], v[80:81], v[238:239] op_sel:[0,1] op_sel_hi:[1,1]
	v_pk_add_f32 v[86:87], v[86:87], v[238:239] op_sel:[0,1] op_sel_hi:[1,1]
	v_pk_add_f32 v[84:85], v[84:85], v[238:239] op_sel:[0,1] op_sel_hi:[1,1]
	v_rcp_f32_e32 v82, v82
	v_rcp_f32_e32 v83, v83
	v_rcp_f32_e32 v80, v80
	v_rcp_f32_e32 v81, v81
	v_rcp_f32_e32 v86, v86
	v_rcp_f32_e32 v87, v87
	v_rcp_f32_e32 v84, v84
	v_rcp_f32_e32 v85, v85
	v_pk_mul_f32 v[78:79], v[78:79], v[82:83]
	v_pk_mul_f32 v[76:77], v[76:77], v[80:81]
	v_pk_mul_f32 v[74:75], v[74:75], v[86:87]
	v_pk_mul_f32 v[72:73], v[72:73], v[84:85]
.LBB0_134:
	s_or_b64 exec, exec, s[60:61]
	v_or_b32_e32 v82, 48, v157
	v_mov_b64_e32 v[80:81], s[4:5]
	v_mad_i64_i32 v[80:81], s[60:61], v82, s81, v[80:81]
	v_lshl_add_u64 v[80:81], v[146:147], 1, v[80:81]
	v_cvt_pk_bf16_f32 v76, v76, v77
	v_cvt_pk_bf16_f32 v77, v78, v79
	v_cvt_pk_bf16_f32 v78, v72, v73
	v_cvt_pk_bf16_f32 v79, v74, v75
	global_store_dwordx4 v[80:81], v[76:79], off
	s_and_saveexec_b64 s[60:61], s[8:9]
	s_cbranch_execz .LBB0_136
	v_pk_mul_f32 v[74:75], v[70:71], s[98:99]
	v_pk_mul_f32 v[72:73], v[68:69], s[98:99]
	v_pk_mul_f32 v[78:79], v[66:67], s[98:99]
	v_pk_mul_f32 v[76:77], v[64:65], s[98:99]
	v_pk_mul_f32 v[74:75], v[70:71], v[74:75]
	v_pk_mul_f32 v[72:73], v[68:69], v[72:73]
	v_pk_mul_f32 v[78:79], v[66:67], v[78:79]
	v_pk_mul_f32 v[76:77], v[64:65], v[76:77]
	v_pk_fma_f32 v[74:75], v[70:71], v[74:75], v[70:71]
	v_pk_fma_f32 v[72:73], v[68:69], v[72:73], v[68:69]
	v_pk_fma_f32 v[78:79], v[66:67], v[78:79], v[66:67]
	v_pk_fma_f32 v[76:77], v[64:65], v[76:77], v[64:65]
	v_pk_mul_f32 v[74:75], v[74:75], s[100:101]
	v_pk_mul_f32 v[72:73], v[72:73], s[100:101]
	v_pk_mul_f32 v[78:79], v[78:79], s[100:101]
	v_pk_mul_f32 v[76:77], v[76:77], s[100:101]
	v_pk_mul_f32 v[74:75], v[74:75], v[238:239] op_sel_hi:[1,0]
	v_pk_mul_f32 v[72:73], v[72:73], v[238:239] op_sel_hi:[1,0]
	v_pk_mul_f32 v[78:79], v[78:79], v[238:239] op_sel_hi:[1,0]
	v_pk_mul_f32 v[76:77], v[76:77], v[238:239] op_sel_hi:[1,0]
	v_exp_f32_e32 v74, v74
	v_exp_f32_e32 v75, v75
	v_exp_f32_e32 v72, v72
	v_exp_f32_e32 v73, v73
	v_exp_f32_e32 v78, v78
	v_exp_f32_e32 v79, v79
	v_exp_f32_e32 v76, v76
	v_exp_f32_e32 v77, v77
	v_pk_add_f32 v[74:75], v[74:75], v[238:239] op_sel:[0,1] op_sel_hi:[1,1]
	v_pk_add_f32 v[72:73], v[72:73], v[238:239] op_sel:[0,1] op_sel_hi:[1,1]
	v_pk_add_f32 v[78:79], v[78:79], v[238:239] op_sel:[0,1] op_sel_hi:[1,1]
	v_pk_add_f32 v[76:77], v[76:77], v[238:239] op_sel:[0,1] op_sel_hi:[1,1]
	v_rcp_f32_e32 v74, v74
	v_rcp_f32_e32 v75, v75
	v_rcp_f32_e32 v72, v72
	v_rcp_f32_e32 v73, v73
	v_rcp_f32_e32 v78, v78
	v_rcp_f32_e32 v79, v79
	v_rcp_f32_e32 v76, v76
	v_rcp_f32_e32 v77, v77
	v_pk_mul_f32 v[70:71], v[70:71], v[74:75]
	v_pk_mul_f32 v[68:69], v[68:69], v[72:73]
	v_pk_mul_f32 v[66:67], v[66:67], v[78:79]
	v_pk_mul_f32 v[64:65], v[64:65], v[76:77]
; __device__ __forceinline__ unsigned pk2(float lo, float hi) { unsigned r; asm("v_cvt_pk_bf16_f32 %0, %1, %2" : "=v"(r) : "v"(lo), "v"(hi)); return r; }
; __device__ __forceinline__ float gelu_t(float x) { return x * __builtin_amdgcn_rcpf(1.f + __expf(-1.5957691216057308f * (x + 0.044715f * x * x * x))); }
;     __device__ __forceinline__ void operator()(const f32x4 (&acc)[2][2][4][2], const Unit& u, int wr, int wc, int fr, int fq) const {
;     ...
;             for (int m = 0; m < 4; ++m) { const int row = row0 + ai * HALF + m * 16; u16* rowp = O + (size_t)row * ldc + col0;
; #pragma unroll
;                 for (int bj = 0; bj < 2; ++bj) { f32x4 v0 = acc[ai][bj][m][0], v1 = acc[ai][bj][m][1];
;                     if (col0 + bj * HALF >= gelu_from) { v0 = (f32x4){gelu_t(v0.x), gelu_t(v0.y), gelu_t(v0.z), gelu_t(v0.w)}; v1 = (f32x4){gelu_t(v1.x), gelu_t(v1.y), gelu_t(v1.z), gelu_t(v1.w)}; }
;                     u32x4 w; w.x = pk2(v0[0], v0[1]); w.y = pk2(v0[2], v0[3]); w.z = pk2(v1[0], v1[1]); w.w = pk2(v1[2], v1[3]);
;                     *(u32x4*)(rowp + bj * HALF) = w;
;                     if (halo != nullptr && m == 3 && fr >= 14) *(u32x4*)(halo + (size_t)((row >> 6) * 2 + (fr - 14)) * ldc + col0 + bj * HALF) = w; } }
.LBB0_136:
	s_or_b64 exec, exec, s[60:61]
	v_cvt_pk_bf16_f32 v68, v68, v69
	v_cvt_pk_bf16_f32 v69, v70, v71
	v_cvt_pk_bf16_f32 v70, v64, v65
	v_cvt_pk_bf16_f32 v71, v66, v67
	global_store_dwordx4 v[80:81], v[68:71], off offset:256
	s_and_saveexec_b64 s[60:61], vcc
	s_cbranch_execz .LBB0_138
	v_pk_mul_f32 v[66:67], v[62:63], s[98:99]
	v_pk_mul_f32 v[64:65], v[60:61], s[98:99]
	v_pk_mul_f32 v[70:71], v[58:59], s[98:99]
	v_pk_mul_f32 v[68:69], v[56:57], s[98:99]
	v_pk_mul_f32 v[66:67], v[62:63], v[66:67]
	v_pk_mul_f32 v[64:65], v[60:61], v[64:65]
	v_pk_mul_f32 v[70:71], v[58:59], v[70:71]
	v_pk_mul_f32 v[68:69], v[56:57], v[68:69]
	v_pk_fma_f32 v[66:67], v[62:63], v[66:67], v[62:63]
	v_pk_fma_f32 v[64:65], v[60:61], v[64:65], v[60:61]
	v_pk_fma_f32 v[70:71], v[58:59], v[70:71], v[58:59]
	v_pk_fma_f32 v[68:69], v[56:57], v[68:69], v[56:57]
	v_pk_mul_f32 v[66:67], v[66:67], s[100:101]
	v_pk_mul_f32 v[64:65], v[64:65], s[100:101]
	v_pk_mul_f32 v[70:71], v[70:71], s[100:101]
	v_pk_mul_f32 v[68:69], v[68:69], s[100:101]
	v_pk_mul_f32 v[66:67], v[66:67], v[238:239] op_sel_hi:[1,0]
	v_pk_mul_f32 v[64:65], v[64:65], v[238:239] op_sel_hi:[1,0]
	v_pk_mul_f32 v[70:71], v[70:71], v[238:239] op_sel_hi:[1,0]
	v_pk_mul_f32 v[68:69], v[68:69], v[238:239] op_sel_hi:[1,0]
	v_exp_f32_e32 v66, v66
	v_exp_f32_e32 v67, v67
	v_exp_f32_e32 v64, v64
	v_exp_f32_e32 v65, v65
	v_exp_f32_e32 v70, v70
	v_exp_f32_e32 v71, v71
	v_exp_f32_e32 v68, v68
	v_exp_f32_e32 v69, v69
	v_pk_add_f32 v[66:67], v[66:67], v[238:239] op_sel:[0,1] op_sel_hi:[1,1]
	v_pk_add_f32 v[64:65], v[64:65], v[238:239] op_sel:[0,1] op_sel_hi:[1,1]
	v_pk_add_f32 v[70:71], v[70:71], v[238:239] op_sel:[0,1] op_sel_hi:[1,1]
	v_pk_add_f32 v[68:69], v[68:69], v[238:239] op_sel:[0,1] op_sel_hi:[1,1]
	v_rcp_f32_e32 v66, v66
	v_rcp_f32_e32 v67, v67
	v_rcp_f32_e32 v64, v64
	v_rcp_f32_e32 v65, v65
	v_rcp_f32_e32 v70, v70
	v_rcp_f32_e32 v71, v71
	v_rcp_f32_e32 v68, v68
	v_rcp_f32_e32 v69, v69
	v_pk_mul_f32 v[62:63], v[62:63], v[66:67]
	v_pk_mul_f32 v[60:61], v[60:61], v[64:65]
	v_pk_mul_f32 v[58:59], v[58:59], v[70:71]
	v_pk_mul_f32 v[56:57], v[56:57], v[68:69]
.LBB0_138:
	s_or_b64 exec, exec, s[60:61]
	v_add_u32_e32 v66, 0x80, v157
	v_mov_b64_e32 v[64:65], s[4:5]
	v_mad_i64_i32 v[64:65], s[60:61], v66, s81, v[64:65]
	v_lshl_add_u64 v[64:65], v[146:147], 1, v[64:65]
	v_cvt_pk_bf16_f32 v60, v60, v61
	v_cvt_pk_bf16_f32 v61, v62, v63
	v_cvt_pk_bf16_f32 v62, v56, v57
	v_cvt_pk_bf16_f32 v63, v58, v59
	global_store_dwordx4 v[64:65], v[60:63], off
	s_and_saveexec_b64 s[60:61], s[8:9]
	s_cbranch_execz .LBB0_140
	v_pk_mul_f32 v[58:59], v[54:55], s[98:99]
	v_pk_mul_f32 v[56:57], v[52:53], s[98:99]
	v_pk_mul_f32 v[62:63], v[50:51], s[98:99]
	v_pk_mul_f32 v[60:61], v[48:49], s[98:99]
	v_pk_mul_f32 v[58:59], v[54:55], v[58:59]
	v_pk_mul_f32 v[56:57], v[52:53], v[56:57]
	v_pk_mul_f32 v[62:63], v[50:51], v[62:63]
	v_pk_mul_f32 v[60:61], v[48:49], v[60:61]
	v_pk_fma_f32 v[58:59], v[54:55], v[58:59], v[54:55]
	v_pk_fma_f32 v[56:57], v[52:53], v[56:57], v[52:53]
	v_pk_fma_f32 v[62:63], v[50:51], v[62:63], v[50:51]
	v_pk_fma_f32 v[60:61], v[48:49], v[60:61], v[48:49]
	v_pk_mul_f32 v[58:59], v[58:59], s[100:101]
	v_pk_mul_f32 v[56:57], v[56:57], s[100:101]
	v_pk_mul_f32 v[62:63], v[62:63], s[100:101]
	v_pk_mul_f32 v[60:61], v[60:61], s[100:101]
	v_pk_mul_f32 v[58:59], v[58:59], v[238:239] op_sel_hi:[1,0]
	v_pk_mul_f32 v[56:57], v[56:57], v[238:239] op_sel_hi:[1,0]
	v_pk_mul_f32 v[62:63], v[62:63], v[238:239] op_sel_hi:[1,0]
	v_pk_mul_f32 v[60:61], v[60:61], v[238:239] op_sel_hi:[1,0]
	v_exp_f32_e32 v58, v58
	v_exp_f32_e32 v59, v59
	v_exp_f32_e32 v56, v56
	v_exp_f32_e32 v57, v57
	v_exp_f32_e32 v62, v62
	v_exp_f32_e32 v63, v63
	v_exp_f32_e32 v60, v60
	v_exp_f32_e32 v61, v61
	v_pk_add_f32 v[58:59], v[58:59], v[238:239] op_sel:[0,1] op_sel_hi:[1,1]
	v_pk_add_f32 v[56:57], v[56:57], v[238:239] op_sel:[0,1] op_sel_hi:[1,1]
	v_pk_add_f32 v[62:63], v[62:63], v[238:239] op_sel:[0,1] op_sel_hi:[1,1]
	v_pk_add_f32 v[60:61], v[60:61], v[238:239] op_sel:[0,1] op_sel_hi:[1,1]
	v_rcp_f32_e32 v58, v58
	v_rcp_f32_e32 v59, v59
	v_rcp_f32_e32 v56, v56
	v_rcp_f32_e32 v57, v57
	v_rcp_f32_e32 v62, v62
	v_rcp_f32_e32 v63, v63
	v_rcp_f32_e32 v60, v60
	v_rcp_f32_e32 v61, v61
	v_pk_mul_f32 v[54:55], v[54:55], v[58:59]
	v_pk_mul_f32 v[52:53], v[52:53], v[56:57]
	v_pk_mul_f32 v[50:51], v[50:51], v[62:63]
	v_pk_mul_f32 v[48:49], v[48:49], v[60:61]
.LBB0_140:
	s_or_b64 exec, exec, s[60:61]
	v_cvt_pk_bf16_f32 v52, v52, v53
	v_cvt_pk_bf16_f32 v53, v54, v55
	v_cvt_pk_bf16_f32 v54, v48, v49
	v_cvt_pk_bf16_f32 v55, v50, v51
	global_store_dwordx4 v[64:65], v[52:55], off offset:256
	s_and_saveexec_b64 s[60:61], vcc
	s_cbranch_execz .LBB0_142
	v_pk_mul_f32 v[50:51], v[46:47], s[98:99]
	v_pk_mul_f32 v[48:49], v[44:45], s[98:99]
	v_pk_mul_f32 v[54:55], v[42:43], s[98:99]
	v_pk_mul_f32 v[52:53], v[40:41], s[98:99]
	v_pk_mul_f32 v[50:51], v[46:47], v[50:51]
	v_pk_mul_f32 v[48:49], v[44:45], v[48:49]
	v_pk_mul_f32 v[54:55], v[42:43], v[54:55]
	v_pk_mul_f32 v[52:53], v[40:41], v[52:53]
	v_pk_fma_f32 v[50:51], v[46:47], v[50:51], v[46:47]
	v_pk_fma_f32 v[48:49], v[44:45], v[48:49], v[44:45]
	v_pk_fma_f32 v[54:55], v[42:43], v[54:55], v[42:43]
	v_pk_fma_f32 v[52:53], v[40:41], v[52:53], v[40:41]
	v_pk_mul_f32 v[50:51], v[50:51], s[100:101]
	v_pk_mul_f32 v[48:49], v[48:49], s[100:101]
	v_pk_mul_f32 v[54:55], v[54:55], s[100:101]
	v_pk_mul_f32 v[52:53], v[52:53], s[100:101]
	v_pk_mul_f32 v[50:51], v[50:51], v[238:239] op_sel_hi:[1,0]
	v_pk_mul_f32 v[48:49], v[48:49], v[238:239] op_sel_hi:[1,0]
	v_pk_mul_f32 v[54:55], v[54:55], v[238:239] op_sel_hi:[1,0]
	v_pk_mul_f32 v[52:53], v[52:53], v[238:239] op_sel_hi:[1,0]
	v_exp_f32_e32 v50, v50
	v_exp_f32_e32 v51, v51
	v_exp_f32_e32 v48, v48
	v_exp_f32_e32 v49, v49
	v_exp_f32_e32 v54, v54
	v_exp_f32_e32 v55, v55
	v_exp_f32_e32 v52, v52
	v_exp_f32_e32 v53, v53
	v_pk_add_f32 v[50:51], v[50:51], v[238:239] op_sel:[0,1] op_sel_hi:[1,1]
	v_pk_add_f32 v[48:49], v[48:49], v[238:239] op_sel:[0,1] op_sel_hi:[1,1]
	v_pk_add_f32 v[54:55], v[54:55], v[238:239] op_sel:[0,1] op_sel_hi:[1,1]
	v_pk_add_f32 v[52:53], v[52:53], v[238:239] op_sel:[0,1] op_sel_hi:[1,1]
	v_rcp_f32_e32 v50, v50
	v_rcp_f32_e32 v51, v51
	v_rcp_f32_e32 v48, v48
	v_rcp_f32_e32 v49, v49
	v_rcp_f32_e32 v54, v54
	v_rcp_f32_e32 v55, v55
	v_rcp_f32_e32 v52, v52
	v_rcp_f32_e32 v53, v53
	v_pk_mul_f32 v[46:47], v[46:47], v[50:51]
	v_pk_mul_f32 v[44:45], v[44:45], v[48:49]
	v_pk_mul_f32 v[42:43], v[42:43], v[54:55]
	v_pk_mul_f32 v[40:41], v[40:41], v[52:53]
; __device__ __forceinline__ unsigned pk2(float lo, float hi) { unsigned r; asm("v_cvt_pk_bf16_f32 %0, %1, %2" : "=v"(r) : "v"(lo), "v"(hi)); return r; }
; __device__ __forceinline__ float gelu_t(float x) { return x * __builtin_amdgcn_rcpf(1.f + __expf(-1.5957691216057308f * (x + 0.044715f * x * x * x))); }
;     __device__ __forceinline__ void operator()(const f32x4 (&acc)[2][2][4][2], const Unit& u, int wr, int wc, int fr, int fq) const {
;     ...
;             for (int m = 0; m < 4; ++m) { const int row = row0 + ai * HALF + m * 16; u16* rowp = O + (size_t)row * ldc + col0;
; #pragma unroll
;                 for (int bj = 0; bj < 2; ++bj) { f32x4 v0 = acc[ai][bj][m][0], v1 = acc[ai][bj][m][1];
;                     if (col0 + bj * HALF >= gelu_from) { v0 = (f32x4){gelu_t(v0.x), gelu_t(v0.y), gelu_t(v0.z), gelu_t(v0.w)}; v1 = (f32x4){gelu_t(v1.x), gelu_t(v1.y), gelu_t(v1.z), gelu_t(v1.w)}; }
;                     u32x4 w; w.x = pk2(v0[0], v0[1]); w.y = pk2(v0[2], v0[3]); w.z = pk2(v1[0], v1[1]); w.w = pk2(v1[2], v1[3]);
;                     *(u32x4*)(rowp + bj * HALF) = w;
;                     if (halo != nullptr && m == 3 && fr >= 14) *(u32x4*)(halo + (size_t)((row >> 6) * 2 + (fr - 14)) * ldc + col0 + bj * HALF) = w; } }
.LBB0_142:
	s_or_b64 exec, exec, s[60:61]
	v_add_u32_e32 v50, 0x90, v157
	v_mov_b64_e32 v[48:49], s[4:5]
	v_mad_i64_i32 v[48:49], s[60:61], v50, s81, v[48:49]
	v_lshl_add_u64 v[48:49], v[146:147], 1, v[48:49]
	v_cvt_pk_bf16_f32 v44, v44, v45
	v_cvt_pk_bf16_f32 v45, v46, v47
	v_cvt_pk_bf16_f32 v46, v40, v41
	v_cvt_pk_bf16_f32 v47, v42, v43
	global_store_dwordx4 v[48:49], v[44:47], off
	s_and_saveexec_b64 s[60:61], s[8:9]
	s_cbranch_execz .LBB0_144
	v_pk_mul_f32 v[42:43], v[38:39], s[98:99]
	v_pk_mul_f32 v[40:41], v[36:37], s[98:99]
	v_pk_mul_f32 v[46:47], v[34:35], s[98:99]
	v_pk_mul_f32 v[44:45], v[32:33], s[98:99]
	v_pk_mul_f32 v[42:43], v[38:39], v[42:43]
	v_pk_mul_f32 v[40:41], v[36:37], v[40:41]
	v_pk_mul_f32 v[46:47], v[34:35], v[46:47]
	v_pk_mul_f32 v[44:45], v[32:33], v[44:45]
	v_pk_fma_f32 v[42:43], v[38:39], v[42:43], v[38:39]
	v_pk_fma_f32 v[40:41], v[36:37], v[40:41], v[36:37]
	v_pk_fma_f32 v[46:47], v[34:35], v[46:47], v[34:35]
	v_pk_fma_f32 v[44:45], v[32:33], v[44:45], v[32:33]
	v_pk_mul_f32 v[42:43], v[42:43], s[100:101]
	v_pk_mul_f32 v[40:41], v[40:41], s[100:101]
	v_pk_mul_f32 v[46:47], v[46:47], s[100:101]
	v_pk_mul_f32 v[44:45], v[44:45], s[100:101]
	v_pk_mul_f32 v[42:43], v[42:43], v[238:239] op_sel_hi:[1,0]
	v_pk_mul_f32 v[40:41], v[40:41], v[238:239] op_sel_hi:[1,0]
	v_pk_mul_f32 v[46:47], v[46:47], v[238:239] op_sel_hi:[1,0]
	v_pk_mul_f32 v[44:45], v[44:45], v[238:239] op_sel_hi:[1,0]
	v_exp_f32_e32 v42, v42
	v_exp_f32_e32 v43, v43
	v_exp_f32_e32 v40, v40
	v_exp_f32_e32 v41, v41
	v_exp_f32_e32 v46, v46
	v_exp_f32_e32 v47, v47
	v_exp_f32_e32 v44, v44
	v_exp_f32_e32 v45, v45
	v_pk_add_f32 v[42:43], v[42:43], v[238:239] op_sel:[0,1] op_sel_hi:[1,1]
	v_pk_add_f32 v[40:41], v[40:41], v[238:239] op_sel:[0,1] op_sel_hi:[1,1]
	v_pk_add_f32 v[46:47], v[46:47], v[238:239] op_sel:[0,1] op_sel_hi:[1,1]
	v_pk_add_f32 v[44:45], v[44:45], v[238:239] op_sel:[0,1] op_sel_hi:[1,1]
	v_rcp_f32_e32 v42, v42
	v_rcp_f32_e32 v43, v43
	v_rcp_f32_e32 v40, v40
	v_rcp_f32_e32 v41, v41
	v_rcp_f32_e32 v46, v46
	v_rcp_f32_e32 v47, v47
	v_rcp_f32_e32 v44, v44
	v_rcp_f32_e32 v45, v45
	v_pk_mul_f32 v[38:39], v[38:39], v[42:43]
	v_pk_mul_f32 v[36:37], v[36:37], v[40:41]
	v_pk_mul_f32 v[34:35], v[34:35], v[46:47]
	v_pk_mul_f32 v[32:33], v[32:33], v[44:45]
.LBB0_144:
	s_or_b64 exec, exec, s[60:61]
	v_cvt_pk_bf16_f32 v36, v36, v37
	v_cvt_pk_bf16_f32 v37, v38, v39
	v_cvt_pk_bf16_f32 v38, v32, v33
	v_cvt_pk_bf16_f32 v39, v34, v35
	global_store_dwordx4 v[48:49], v[36:39], off offset:256
	s_and_saveexec_b64 s[60:61], vcc
	s_cbranch_execz .LBB0_146
	v_pk_mul_f32 v[34:35], v[30:31], s[98:99]
	v_pk_mul_f32 v[32:33], v[28:29], s[98:99]
	v_pk_mul_f32 v[38:39], v[26:27], s[98:99]
	v_pk_mul_f32 v[36:37], v[24:25], s[98:99]
	v_pk_mul_f32 v[34:35], v[30:31], v[34:35]
	v_pk_mul_f32 v[32:33], v[28:29], v[32:33]
	v_pk_mul_f32 v[38:39], v[26:27], v[38:39]
	v_pk_mul_f32 v[36:37], v[24:25], v[36:37]
	v_pk_fma_f32 v[34:35], v[30:31], v[34:35], v[30:31]
	v_pk_fma_f32 v[32:33], v[28:29], v[32:33], v[28:29]
	v_pk_fma_f32 v[38:39], v[26:27], v[38:39], v[26:27]
	v_pk_fma_f32 v[36:37], v[24:25], v[36:37], v[24:25]
	v_pk_mul_f32 v[34:35], v[34:35], s[100:101]
	v_pk_mul_f32 v[32:33], v[32:33], s[100:101]
	v_pk_mul_f32 v[38:39], v[38:39], s[100:101]
	v_pk_mul_f32 v[36:37], v[36:37], s[100:101]
	v_pk_mul_f32 v[34:35], v[34:35], v[238:239] op_sel_hi:[1,0]
	v_pk_mul_f32 v[32:33], v[32:33], v[238:239] op_sel_hi:[1,0]
	v_pk_mul_f32 v[38:39], v[38:39], v[238:239] op_sel_hi:[1,0]
	v_pk_mul_f32 v[36:37], v[36:37], v[238:239] op_sel_hi:[1,0]
	v_exp_f32_e32 v34, v34
	v_exp_f32_e32 v35, v35
	v_exp_f32_e32 v32, v32
	v_exp_f32_e32 v33, v33
	v_exp_f32_e32 v38, v38
	v_exp_f32_e32 v39, v39
	v_exp_f32_e32 v36, v36
	v_exp_f32_e32 v37, v37
	v_pk_add_f32 v[34:35], v[34:35], v[238:239] op_sel:[0,1] op_sel_hi:[1,1]
	v_pk_add_f32 v[32:33], v[32:33], v[238:239] op_sel:[0,1] op_sel_hi:[1,1]
	v_pk_add_f32 v[38:39], v[38:39], v[238:239] op_sel:[0,1] op_sel_hi:[1,1]
	v_pk_add_f32 v[36:37], v[36:37], v[238:239] op_sel:[0,1] op_sel_hi:[1,1]
	v_rcp_f32_e32 v34, v34
	v_rcp_f32_e32 v35, v35
	v_rcp_f32_e32 v32, v32
	v_rcp_f32_e32 v33, v33
	v_rcp_f32_e32 v38, v38
	v_rcp_f32_e32 v39, v39
	v_rcp_f32_e32 v36, v36
	v_rcp_f32_e32 v37, v37
	v_pk_mul_f32 v[30:31], v[30:31], v[34:35]
	v_pk_mul_f32 v[28:29], v[28:29], v[32:33]
	v_pk_mul_f32 v[26:27], v[26:27], v[38:39]
	v_pk_mul_f32 v[24:25], v[24:25], v[36:37]
; __device__ __forceinline__ unsigned pk2(float lo, float hi) { unsigned r; asm("v_cvt_pk_bf16_f32 %0, %1, %2" : "=v"(r) : "v"(lo), "v"(hi)); return r; }
; __device__ __forceinline__ float gelu_t(float x) { return x * __builtin_amdgcn_rcpf(1.f + __expf(-1.5957691216057308f * (x + 0.044715f * x * x * x))); }
;     __device__ __forceinline__ void operator()(const f32x4 (&acc)[2][2][4][2], const Unit& u, int wr, int wc, int fr, int fq) const {
;     ...
;             for (int m = 0; m < 4; ++m) { const int row = row0 + ai * HALF + m * 16; u16* rowp = O + (size_t)row * ldc + col0;
; #pragma unroll
;                 for (int bj = 0; bj < 2; ++bj) { f32x4 v0 = acc[ai][bj][m][0], v1 = acc[ai][bj][m][1];
;                     if (col0 + bj * HALF >= gelu_from) { v0 = (f32x4){gelu_t(v0.x), gelu_t(v0.y), gelu_t(v0.z), gelu_t(v0.w)}; v1 = (f32x4){gelu_t(v1.x), gelu_t(v1.y), gelu_t(v1.z), gelu_t(v1.w)}; }
;                     u32x4 w; w.x = pk2(v0[0], v0[1]); w.y = pk2(v0[2], v0[3]); w.z = pk2(v1[0], v1[1]); w.w = pk2(v1[2], v1[3]);
;                     *(u32x4*)(rowp + bj * HALF) = w;
;                     if (halo != nullptr && m == 3 && fr >= 14) *(u32x4*)(halo + (size_t)((row >> 6) * 2 + (fr - 14)) * ldc + col0 + bj * HALF) = w; } }
.LBB0_146:
	s_or_b64 exec, exec, s[60:61]
	v_add_u32_e32 v34, 0xa0, v157
	v_mov_b64_e32 v[32:33], s[4:5]
	v_mad_i64_i32 v[32:33], s[60:61], v34, s81, v[32:33]
	v_lshl_add_u64 v[32:33], v[146:147], 1, v[32:33]
	v_cvt_pk_bf16_f32 v28, v28, v29
	v_cvt_pk_bf16_f32 v29, v30, v31
	v_cvt_pk_bf16_f32 v30, v24, v25
	v_cvt_pk_bf16_f32 v31, v26, v27
	global_store_dwordx4 v[32:33], v[28:31], off
	s_and_saveexec_b64 s[60:61], s[8:9]
	s_cbranch_execz .LBB0_148
	v_pk_mul_f32 v[26:27], v[22:23], s[98:99]
	v_pk_mul_f32 v[24:25], v[20:21], s[98:99]
	v_pk_mul_f32 v[30:31], v[18:19], s[98:99]
	v_pk_mul_f32 v[28:29], v[16:17], s[98:99]
	v_pk_mul_f32 v[26:27], v[22:23], v[26:27]
	v_pk_mul_f32 v[24:25], v[20:21], v[24:25]
	v_pk_mul_f32 v[30:31], v[18:19], v[30:31]
	v_pk_mul_f32 v[28:29], v[16:17], v[28:29]
	v_pk_fma_f32 v[26:27], v[22:23], v[26:27], v[22:23]
	v_pk_fma_f32 v[24:25], v[20:21], v[24:25], v[20:21]
	v_pk_fma_f32 v[30:31], v[18:19], v[30:31], v[18:19]
	v_pk_fma_f32 v[28:29], v[16:17], v[28:29], v[16:17]
	v_pk_mul_f32 v[26:27], v[26:27], s[100:101]
	v_pk_mul_f32 v[24:25], v[24:25], s[100:101]
	v_pk_mul_f32 v[30:31], v[30:31], s[100:101]
	v_pk_mul_f32 v[28:29], v[28:29], s[100:101]
	v_pk_mul_f32 v[26:27], v[26:27], v[238:239] op_sel_hi:[1,0]
	v_pk_mul_f32 v[24:25], v[24:25], v[238:239] op_sel_hi:[1,0]
	v_pk_mul_f32 v[30:31], v[30:31], v[238:239] op_sel_hi:[1,0]
	v_pk_mul_f32 v[28:29], v[28:29], v[238:239] op_sel_hi:[1,0]
	v_exp_f32_e32 v26, v26
	v_exp_f32_e32 v27, v27
	v_exp_f32_e32 v24, v24
	v_exp_f32_e32 v25, v25
	v_exp_f32_e32 v30, v30
	v_exp_f32_e32 v31, v31
	v_exp_f32_e32 v28, v28
	v_exp_f32_e32 v29, v29
	v_pk_add_f32 v[26:27], v[26:27], v[238:239] op_sel:[0,1] op_sel_hi:[1,1]
	v_pk_add_f32 v[24:25], v[24:25], v[238:239] op_sel:[0,1] op_sel_hi:[1,1]
	v_pk_add_f32 v[30:31], v[30:31], v[238:239] op_sel:[0,1] op_sel_hi:[1,1]
	v_pk_add_f32 v[28:29], v[28:29], v[238:239] op_sel:[0,1] op_sel_hi:[1,1]
	v_rcp_f32_e32 v26, v26
	v_rcp_f32_e32 v27, v27
	v_rcp_f32_e32 v24, v24
	v_rcp_f32_e32 v25, v25
	v_rcp_f32_e32 v30, v30
	v_rcp_f32_e32 v31, v31
	v_rcp_f32_e32 v28, v28
	v_rcp_f32_e32 v29, v29
	v_pk_mul_f32 v[22:23], v[22:23], v[26:27]
	v_pk_mul_f32 v[20:21], v[20:21], v[24:25]
	v_pk_mul_f32 v[18:19], v[18:19], v[30:31]
	v_pk_mul_f32 v[16:17], v[16:17], v[28:29]
.LBB0_148:
	s_or_b64 exec, exec, s[60:61]
	v_cvt_pk_bf16_f32 v20, v20, v21
	v_cvt_pk_bf16_f32 v21, v22, v23
	v_cvt_pk_bf16_f32 v22, v16, v17
	v_cvt_pk_bf16_f32 v23, v18, v19
	global_store_dwordx4 v[32:33], v[20:23], off offset:256
	s_and_saveexec_b64 s[60:61], vcc
	s_cbranch_execz .LBB0_150
	v_pk_mul_f32 v[18:19], v[14:15], s[98:99]
	v_pk_mul_f32 v[16:17], v[12:13], s[98:99]
	v_pk_mul_f32 v[22:23], v[10:11], s[98:99]
	v_pk_mul_f32 v[20:21], v[8:9], s[98:99]
	v_pk_mul_f32 v[18:19], v[14:15], v[18:19]
	v_pk_mul_f32 v[16:17], v[12:13], v[16:17]
	v_pk_mul_f32 v[22:23], v[10:11], v[22:23]
	v_pk_mul_f32 v[20:21], v[8:9], v[20:21]
	v_pk_fma_f32 v[18:19], v[14:15], v[18:19], v[14:15]
	v_pk_fma_f32 v[16:17], v[12:13], v[16:17], v[12:13]
	v_pk_fma_f32 v[22:23], v[10:11], v[22:23], v[10:11]
	v_pk_fma_f32 v[20:21], v[8:9], v[20:21], v[8:9]
	v_pk_mul_f32 v[18:19], v[18:19], s[100:101]
	v_pk_mul_f32 v[16:17], v[16:17], s[100:101]
	v_pk_mul_f32 v[22:23], v[22:23], s[100:101]
	v_pk_mul_f32 v[20:21], v[20:21], s[100:101]
	v_pk_mul_f32 v[18:19], v[18:19], v[238:239] op_sel_hi:[1,0]
	v_pk_mul_f32 v[16:17], v[16:17], v[238:239] op_sel_hi:[1,0]
	v_pk_mul_f32 v[22:23], v[22:23], v[238:239] op_sel_hi:[1,0]
	v_pk_mul_f32 v[20:21], v[20:21], v[238:239] op_sel_hi:[1,0]
	v_exp_f32_e32 v18, v18
	v_exp_f32_e32 v19, v19
	v_exp_f32_e32 v16, v16
	v_exp_f32_e32 v17, v17
	v_exp_f32_e32 v22, v22
	v_exp_f32_e32 v23, v23
	v_exp_f32_e32 v20, v20
	v_exp_f32_e32 v21, v21
	v_pk_add_f32 v[18:19], v[18:19], v[238:239] op_sel:[0,1] op_sel_hi:[1,1]
	v_pk_add_f32 v[16:17], v[16:17], v[238:239] op_sel:[0,1] op_sel_hi:[1,1]
	v_pk_add_f32 v[22:23], v[22:23], v[238:239] op_sel:[0,1] op_sel_hi:[1,1]
	v_pk_add_f32 v[20:21], v[20:21], v[238:239] op_sel:[0,1] op_sel_hi:[1,1]
	v_rcp_f32_e32 v18, v18
	v_rcp_f32_e32 v19, v19
	v_rcp_f32_e32 v16, v16
	v_rcp_f32_e32 v17, v17
	v_rcp_f32_e32 v22, v22
	v_rcp_f32_e32 v23, v23
	v_rcp_f32_e32 v20, v20
	v_rcp_f32_e32 v21, v21
	v_pk_mul_f32 v[14:15], v[14:15], v[18:19]
	v_pk_mul_f32 v[12:13], v[12:13], v[16:17]
	v_pk_mul_f32 v[10:11], v[10:11], v[22:23]
	v_pk_mul_f32 v[8:9], v[8:9], v[20:21]
.LBB0_150:
	s_or_b64 exec, exec, s[60:61]
	v_add_u32_e32 v18, 0xb0, v157
	v_mov_b64_e32 v[16:17], s[4:5]
	v_mad_i64_i32 v[16:17], s[60:61], v18, s81, v[16:17]
	v_lshl_add_u64 v[16:17], v[146:147], 1, v[16:17]
	v_cvt_pk_bf16_f32 v12, v12, v13
	v_cvt_pk_bf16_f32 v13, v14, v15
	v_cvt_pk_bf16_f32 v14, v8, v9
	v_cvt_pk_bf16_f32 v15, v10, v11
	global_store_dwordx4 v[16:17], v[12:15], off
	s_and_saveexec_b64 s[60:61], s[8:9]
	s_cbranch_execz .LBB0_111
	v_pk_mul_f32 v[10:11], v[6:7], s[98:99]
	v_pk_mul_f32 v[8:9], v[4:5], s[98:99]
	v_pk_mul_f32 v[14:15], v[2:3], s[98:99]
	v_pk_mul_f32 v[12:13], v[0:1], s[98:99]
	v_pk_mul_f32 v[10:11], v[6:7], v[10:11]
	v_pk_mul_f32 v[8:9], v[4:5], v[8:9]
	v_pk_mul_f32 v[14:15], v[2:3], v[14:15]
	v_pk_mul_f32 v[12:13], v[0:1], v[12:13]
	v_pk_fma_f32 v[10:11], v[6:7], v[10:11], v[6:7]
	v_pk_fma_f32 v[8:9], v[4:5], v[8:9], v[4:5]
	v_pk_fma_f32 v[14:15], v[2:3], v[14:15], v[2:3]
	v_pk_fma_f32 v[12:13], v[0:1], v[12:13], v[0:1]
	v_pk_mul_f32 v[10:11], v[10:11], s[100:101]
	v_pk_mul_f32 v[8:9], v[8:9], s[100:101]
	v_pk_mul_f32 v[14:15], v[14:15], s[100:101]
	v_pk_mul_f32 v[12:13], v[12:13], s[100:101]
	v_pk_mul_f32 v[10:11], v[10:11], v[238:239] op_sel_hi:[1,0]
	v_pk_mul_f32 v[8:9], v[8:9], v[238:239] op_sel_hi:[1,0]
	v_pk_mul_f32 v[14:15], v[14:15], v[238:239] op_sel_hi:[1,0]
	v_pk_mul_f32 v[12:13], v[12:13], v[238:239] op_sel_hi:[1,0]
	v_exp_f32_e32 v10, v10
	v_exp_f32_e32 v11, v11
	v_exp_f32_e32 v8, v8
	v_exp_f32_e32 v9, v9
	v_exp_f32_e32 v14, v14
	v_exp_f32_e32 v15, v15
	v_exp_f32_e32 v12, v12
	v_exp_f32_e32 v13, v13
	v_pk_add_f32 v[10:11], v[10:11], v[238:239] op_sel:[0,1] op_sel_hi:[1,1]
	v_pk_add_f32 v[8:9], v[8:9], v[238:239] op_sel:[0,1] op_sel_hi:[1,1]
	v_pk_add_f32 v[14:15], v[14:15], v[238:239] op_sel:[0,1] op_sel_hi:[1,1]
	v_pk_add_f32 v[12:13], v[12:13], v[238:239] op_sel:[0,1] op_sel_hi:[1,1]
	v_rcp_f32_e32 v10, v10
	v_rcp_f32_e32 v11, v11
	v_rcp_f32_e32 v8, v8
	v_rcp_f32_e32 v9, v9
	v_rcp_f32_e32 v14, v14
	v_rcp_f32_e32 v15, v15
	v_rcp_f32_e32 v12, v12
	v_rcp_f32_e32 v13, v13
	v_pk_mul_f32 v[6:7], v[6:7], v[10:11]
	v_pk_mul_f32 v[4:5], v[4:5], v[8:9]
	v_pk_mul_f32 v[2:3], v[2:3], v[14:15]
	v_pk_mul_f32 v[0:1], v[0:1], v[12:13]
	s_branch .LBB0_111
